# FFN1 epilogue: second conv-parameter group's loads stay in flight behind the first group's arithmetic (counted vmcnt instead of vmcnt(0)); on top of peeled first k-iteration
# speedup vs baseline: 1.0242x; 1.0000x over previous
; #define LAS __attribute__((address_space(3)))
; __device__ __forceinline__ float sigmoidf_(float x) { return __builtin_amdgcn_rcpf(1.0f + __expf(-x)); }
;     __device__ __forceinline__ void operator()(AccRef acc, const Unit& u, int wr, int wc, int fr, int fq) const {
;     ...
;                 f32x4 h2v = (f32x4){0.f, 0.f, 0.f, 0.f}, h3v = h2v, h2g = h2v, h3g = h2v;
;                 const int pb = ai * 2 + wr - 1;
;                 if (pb >= 0 && fr == 0) { const LAS float* xp = xch + (pb * 2) * 256 + clb + 4 * n;
;                     h2v = *(const LAS f32x4*)(xp); h3v = *(const LAS f32x4*)(xp + 256); h2g = *(const LAS f32x4*)(xp + 128); h3g = *(const LAS f32x4*)(xp + 256 + 128); }
;                 float o[4][4];
; #pragma unroll
;                 for (int j = 0; j < 4; ++j) {
;                     const float v0 = acc[ai][0][0][n][j], v1 = acc[ai][0][1][n][j], v2 = acc[ai][0][2][n][j], v3 = acc[ai][0][3][n][j];
;                     const float g0 = acc[ai][1][0][n][j], g1 = acc[ai][1][1][n][j], g2 = acc[ai][1][2][n][j], g3 = acc[ai][1][3][n][j];
;                     const float pv3 = dpp_upd<0x111>(h3v[j], v3), pv2 = dpp_upd<0x111>(h2v[j], v2), pg3 = dpp_upd<0x111>(h3g[j], g3), pg2 = dpp_upd<0x111>(h2g[j], g2);
;                     const float hv0 = bvv[j] + w2v[j] * v0 + w1v[j] * pv3 + w0v[j] * pv2, hv1 = bvv[j] + w2v[j] * v1 + w1v[j] * v0 + w0v[j] * pv3;
;                     const float hv2 = bvv[j] + w2v[j] * v2 + w1v[j] * v1 + w0v[j] * v0, hv3 = bvv[j] + w2v[j] * v3 + w1v[j] * v2 + w0v[j] * v1;
;                     const float hg0 = bvg[j] + w2g[j] * g0 + w1g[j] * pg3 + w0g[j] * pg2, hg1 = bvg[j] + w2g[j] * g1 + w1g[j] * g0 + w0g[j] * pg3;
;                     const float hg2 = bvg[j] + w2g[j] * g2 + w1g[j] * g1 + w0g[j] * g0, hg3 = bvg[j] + w2g[j] * g3 + w1g[j] * g2 + w0g[j] * g1;
;                     o[0][j] = hg0 * sigmoidf_(hg0) * hv0; o[1][j] = hg1 * sigmoidf_(hg1) * hv1; o[2][j] = hg2 * sigmoidf_(hg2) * hv2; o[3][j] = hg3 * sigmoidf_(hg3) * hv3; }
; #pragma unroll
;                 for (int m = 0; m < 4; ++m) { u32x2 w; w.x = cvt_pk_bf16(o[m][0], o[m][1]); w.y = cvt_pk_bf16(o[m][2], o[m][3]);
;                     *(u32x2*)(Aout + (size_t)(row0 + ai * 128 + m) * FH + hc0 + 4 * n) = w; } } }
.LBB0_318:
	s_or_b64 exec, exec, s[36:37]
	s_waitcnt lgkmcnt(0)
	v_mov_b32_dpp v198, v140 row_shr:1 row_mask:0xf bank_mask:0xf
	v_mov_b32_dpp v199, v141 row_shr:1 row_mask:0xf bank_mask:0xf
	s_waitcnt vmcnt(8)
	v_pk_fma_f32 v[248:249], v[152:153], v[184:185], v[188:189]
	v_mov_b32_dpp v206, v128 row_shr:1 row_mask:0xf bank_mask:0xf
	v_mov_b32_dpp v207, v129 row_shr:1 row_mask:0xf bank_mask:0xf
	v_pk_fma_f32 v[248:249], v[180:181], v[198:199], v[248:249]
	v_mov_b32_dpp v194, v148 row_shr:1 row_mask:0xf bank_mask:0xf
	v_pk_fma_f32 v[206:207], v[176:177], v[206:207], v[248:249]
	v_mov_b32_dpp v195, v149 row_shr:1 row_mask:0xf bank_mask:0xf
	v_mul_f32_e32 v193, 0xbfb8aa3b, v206
	v_exp_f32_e32 v193, v193
	v_mul_f32_e32 v247, 0xbfb8aa3b, v207
	v_exp_f32_e32 v247, v247
	v_pk_fma_f32 v[250:251], v[156:157], v[168:169], v[172:173]
	v_add_f32_e32 v193, 1.0, v193
	v_rcp_f32_e32 v248, v193
	v_add_f32_e32 v193, 1.0, v247
	v_rcp_f32_e32 v249, v193
	v_mov_b32_dpp v202, v136 row_shr:1 row_mask:0xf bank_mask:0xf
	v_mov_b32_dpp v203, v137 row_shr:1 row_mask:0xf bank_mask:0xf
	v_pk_fma_f32 v[250:251], v[164:165], v[194:195], v[250:251]
	v_pk_mul_f32 v[206:207], v[206:207], v[248:249]
	v_pk_fma_f32 v[202:203], v[160:161], v[202:203], v[250:251]
	v_mov_b32_dpp v200, v142 row_shr:1 row_mask:0xf bank_mask:0xf
	v_mov_b32_dpp v201, v143 row_shr:1 row_mask:0xf bank_mask:0xf
	v_pk_mul_f32 v[202:203], v[202:203], v[206:207]
	v_pk_fma_f32 v[206:207], v[154:155], v[186:187], v[190:191]
	v_mov_b32_dpp v208, v130 row_shr:1 row_mask:0xf bank_mask:0xf
	v_mov_b32_dpp v209, v131 row_shr:1 row_mask:0xf bank_mask:0xf
	v_pk_fma_f32 v[206:207], v[182:183], v[200:201], v[206:207]
	v_mov_b32_dpp v196, v150 row_shr:1 row_mask:0xf bank_mask:0xf
	v_pk_fma_f32 v[206:207], v[178:179], v[208:209], v[206:207]
	v_mov_b32_dpp v197, v151 row_shr:1 row_mask:0xf bank_mask:0xf
	v_mul_f32_e32 v193, 0xbfb8aa3b, v206
	v_exp_f32_e32 v193, v193
	v_mul_f32_e32 v208, 0xbfb8aa3b, v207
	v_exp_f32_e32 v209, v208
	v_cvt_pk_bf16_f32 v208, v202, v203
	v_add_f32_e32 v193, 1.0, v193
	v_rcp_f32_e32 v202, v193
	v_add_f32_e32 v193, 1.0, v209
	v_rcp_f32_e32 v203, v193
	v_pk_fma_f32 v[248:249], v[158:159], v[170:171], v[174:175]
	v_mov_b32_dpp v204, v138 row_shr:1 row_mask:0xf bank_mask:0xf
	v_mov_b32_dpp v205, v139 row_shr:1 row_mask:0xf bank_mask:0xf
	v_pk_fma_f32 v[248:249], v[166:167], v[196:197], v[248:249]
	v_pk_mul_f32 v[202:203], v[206:207], v[202:203]
	v_pk_fma_f32 v[204:205], v[162:163], v[204:205], v[248:249]
	v_lshl_add_u32 v246, s34, 8, v236
	v_pk_mul_f32 v[202:203], v[204:205], v[202:203]
	v_lshlrev_b64 v[204:205], 1, v[232:233]
	v_pk_fma_f32 v[232:233], v[132:133], v[184:185], v[188:189]
	v_mov_b64_e32 v[206:207], s[60:61]
	v_pk_fma_f32 v[232:233], v[152:153], v[180:181], v[232:233]
	v_cvt_pk_bf16_f32 v209, v202, v203
	v_pk_fma_f32 v[198:199], v[176:177], v[198:199], v[232:233]
	v_mad_i64_i32 v[202:203], s[34:35], v246, s74, v[206:207]
	v_mul_f32_e32 v193, 0xbfb8aa3b, v198
	v_exp_f32_e32 v193, v193
	v_mul_f32_e32 v232, 0xbfb8aa3b, v199
	v_exp_f32_e32 v232, v232
	v_lshl_add_u64 v[202:203], v[202:203], 0, v[204:205]
	v_add_f32_e32 v193, 1.0, v193
	global_store_dwordx2 v[202:203], v[208:209], off
	v_rcp_f32_e32 v208, v193
	v_add_f32_e32 v193, 1.0, v232
	v_rcp_f32_e32 v209, v193
	v_pk_fma_f32 v[232:233], v[144:145], v[168:169], v[172:173]
	v_pk_fma_f32 v[140:141], v[140:141], v[184:185], v[188:189]
	v_pk_fma_f32 v[232:233], v[156:157], v[164:165], v[232:233]
	v_pk_mul_f32 v[198:199], v[198:199], v[208:209]
	v_pk_fma_f32 v[194:195], v[160:161], v[194:195], v[232:233]
	v_pk_fma_f32 v[208:209], v[146:147], v[170:171], v[174:175]
	v_pk_mul_f32 v[194:195], v[194:195], v[198:199]
	v_pk_fma_f32 v[198:199], v[134:135], v[186:187], v[190:191]
	v_pk_fma_f32 v[208:209], v[158:159], v[166:167], v[208:209]
	v_pk_fma_f32 v[198:199], v[154:155], v[182:183], v[198:199]
	v_pk_fma_f32 v[196:197], v[162:163], v[196:197], v[208:209]
	v_pk_fma_f32 v[198:199], v[178:179], v[200:201], v[198:199]
	v_cvt_pk_bf16_f32 v194, v194, v195
	v_mul_f32_e32 v193, 0xbfb8aa3b, v198
	v_exp_f32_e32 v193, v193
	v_mul_f32_e32 v200, 0xbfb8aa3b, v199
	v_exp_f32_e32 v201, v200
	v_pk_fma_f32 v[148:149], v[148:149], v[168:169], v[172:173]
	v_add_f32_e32 v193, 1.0, v193
; #define LAS __attribute__((address_space(3)))
; __device__ __forceinline__ float sigmoidf_(float x) { return __builtin_amdgcn_rcpf(1.0f + __expf(-x)); }
;     __device__ __forceinline__ void operator()(AccRef acc, const Unit& u, int wr, int wc, int fr, int fq) const {
;     ...
;                 f32x4 h2v = (f32x4){0.f, 0.f, 0.f, 0.f}, h3v = h2v, h2g = h2v, h3g = h2v;
;                 const int pb = ai * 2 + wr - 1;
;                 if (pb >= 0 && fr == 0) { const LAS float* xp = xch + (pb * 2) * 256 + clb + 4 * n;
;                     h2v = *(const LAS f32x4*)(xp); h3v = *(const LAS f32x4*)(xp + 256); h2g = *(const LAS f32x4*)(xp + 128); h3g = *(const LAS f32x4*)(xp + 256 + 128); }
;     ...
;                     o[0][j] = hg0 * sigmoidf_(hg0) * hv0; o[1][j] = hg1 * sigmoidf_(hg1) * hv1; o[2][j] = hg2 * sigmoidf_(hg2) * hv2; o[3][j] = hg3 * sigmoidf_(hg3) * hv3; }
; #pragma unroll
;                 for (int m = 0; m < 4; ++m) { u32x2 w; w.x = cvt_pk_bf16(o[m][0], o[m][1]); w.y = cvt_pk_bf16(o[m][2], o[m][3]);
;                     *(u32x2*)(Aout + (size_t)(row0 + ai * 128 + m) * FH + hc0 + 4 * n) = w; } } }
	v_rcp_f32_e32 v200, v193
	v_add_f32_e32 v193, 1.0, v201
	v_rcp_f32_e32 v201, v193
	v_or_b32_e32 v193, 1, v246
	v_pk_mul_f32 v[198:199], v[198:199], v[200:201]
	s_nop 0
	v_pk_mul_f32 v[196:197], v[196:197], v[198:199]
	v_pk_fma_f32 v[198:199], v[128:129], v[184:185], v[188:189]
	v_cvt_pk_bf16_f32 v195, v196, v197
	v_pk_fma_f32 v[198:199], v[132:133], v[180:181], v[198:199]
	v_mad_i64_i32 v[196:197], s[34:35], v193, s74, v[206:207]
	v_pk_fma_f32 v[152:153], v[152:153], v[176:177], v[198:199]
	v_lshl_add_u64 v[196:197], v[196:197], 0, v[204:205]
	v_mul_f32_e32 v193, 0xbfb8aa3b, v152
	v_exp_f32_e32 v193, v193
	v_mul_f32_e32 v198, 0xbfb8aa3b, v153
	v_exp_f32_e32 v198, v198
	global_store_dwordx2 v[196:197], v[194:195], off
	v_add_f32_e32 v193, 1.0, v193
	v_rcp_f32_e32 v194, v193
	v_add_f32_e32 v193, 1.0, v198
	v_rcp_f32_e32 v195, v193
	v_pk_fma_f32 v[198:199], v[136:137], v[168:169], v[172:173]
	v_pk_fma_f32 v[128:129], v[128:129], v[180:181], v[140:141]
	v_pk_fma_f32 v[198:199], v[144:145], v[164:165], v[198:199]
	v_pk_fma_f32 v[128:129], v[132:133], v[176:177], v[128:129]
	v_pk_fma_f32 v[156:157], v[156:157], v[160:161], v[198:199]
	v_pk_mul_f32 v[152:153], v[152:153], v[194:195]
	v_mul_f32_e32 v132, 0xbfb8aa3b, v128
	v_pk_mul_f32 v[152:153], v[156:157], v[152:153]
	v_pk_fma_f32 v[156:157], v[130:131], v[186:187], v[190:191]
	v_exp_f32_e32 v140, v132
	v_pk_fma_f32 v[132:133], v[142:143], v[186:187], v[190:191]
	v_pk_fma_f32 v[156:157], v[134:135], v[182:183], v[156:157]
	v_pk_fma_f32 v[130:131], v[130:131], v[182:183], v[132:133]
	v_pk_fma_f32 v[154:155], v[154:155], v[178:179], v[156:157]
	v_pk_fma_f32 v[130:131], v[134:135], v[178:179], v[130:131]
	v_mul_f32_e32 v156, 0xbfb8aa3b, v154
	v_mul_f32_e32 v141, 0xbfb8aa3b, v129
	v_mul_f32_e32 v132, 0xbfb8aa3b, v130
	v_mul_f32_e32 v133, 0xbfb8aa3b, v131
	v_exp_f32_e32 v157, v156
	v_mul_f32_e32 v156, 0xbfb8aa3b, v155
	v_exp_f32_e32 v141, v141
	v_exp_f32_e32 v132, v132
	v_exp_f32_e32 v133, v133
	v_exp_f32_e32 v193, v156
	v_add_f32_e32 v140, 1.0, v140
	v_add_f32_e32 v141, 1.0, v141
	v_add_f32_e32 v132, 1.0, v132
	v_add_f32_e32 v133, 1.0, v133
	v_cvt_pk_bf16_f32 v156, v152, v153
	v_add_f32_e32 v152, 1.0, v157
	v_add_f32_e32 v153, 1.0, v193
	v_rcp_f32_e32 v140, v140
	v_rcp_f32_e32 v141, v141
	v_rcp_f32_e32 v132, v132
	v_rcp_f32_e32 v133, v133
	v_rcp_f32_e32 v152, v152
	v_rcp_f32_e32 v153, v153
	v_pk_fma_f32 v[142:143], v[150:151], v[170:171], v[174:175]
	v_pk_fma_f32 v[194:195], v[138:139], v[170:171], v[174:175]
	v_pk_fma_f32 v[136:137], v[136:137], v[164:165], v[148:149]
	v_pk_fma_f32 v[134:135], v[138:139], v[166:167], v[142:143]
	v_pk_fma_f32 v[194:195], v[146:147], v[166:167], v[194:195]
	v_pk_fma_f32 v[136:137], v[144:145], v[160:161], v[136:137]
	v_pk_mul_f32 v[128:129], v[128:129], v[140:141]
	v_pk_fma_f32 v[134:135], v[146:147], v[162:163], v[134:135]
	v_pk_mul_f32 v[130:131], v[130:131], v[132:133]
	v_pk_fma_f32 v[158:159], v[158:159], v[162:163], v[194:195]
	v_pk_mul_f32 v[152:153], v[154:155], v[152:153]
	v_pk_mul_f32 v[128:129], v[136:137], v[128:129]
	v_pk_mul_f32 v[130:131], v[134:135], v[130:131]
	v_pk_mul_f32 v[152:153], v[158:159], v[152:153]
	v_cvt_pk_bf16_f32 v128, v128, v129
	v_cvt_pk_bf16_f32 v129, v130, v131
	v_or_b32_e32 v130, 3, v246
	v_cvt_pk_bf16_f32 v157, v152, v153
	v_or_b32_e32 v152, 2, v246
	v_mad_i64_i32 v[130:131], s[34:35], v130, s74, v[206:207]
	v_mad_i64_i32 v[152:153], s[34:35], v152, s74, v[206:207]
	v_lshl_add_u64 v[140:141], v[130:131], 0, v[204:205]
	v_lshl_add_u64 v[152:153], v[152:153], 0, v[204:205]
	global_store_dwordx2 v[140:141], v[128:129], off
	v_mov_b32_e32 v193, 0
	v_mov_b32_e32 v194, 0
	v_mov_b32_e32 v195, 0
	v_mov_b32_e32 v136, 0
	v_mov_b32_e32 v137, 0
	v_mov_b32_e32 v138, 0
	v_mov_b32_e32 v139, 0
	v_mov_b32_e32 v128, 0
	v_mov_b32_e32 v129, 0
	v_mov_b32_e32 v130, 0
	v_mov_b32_e32 v131, 0
	v_mov_b32_e32 v132, 0
	v_mov_b32_e32 v133, 0
	v_mov_b32_e32 v134, 0
	v_mov_b32_e32 v135, 0
	global_store_dwordx2 v[152:153], v[156:157], off
	s_and_saveexec_b64 s[34:35], s[22:23]
	s_cbranch_execz .LBB0_320
	ds_read_b128 v[132:135], v237 offset:2048
	ds_read_b128 v[136:139], v237 offset:2560
	ds_read_b128 v[128:131], v237 offset:3072
	ds_read_b128 v[192:195], v237 offset:3584

;     __device__ __forceinline__ void operator()(AccRef acc, const Unit& u, int wr, int wc, int fr, int fq) const {
;     ...
;         for (int n = 0; n < 2; ++n) {
;             const f32x4 w0v = cwv[n][0], w1v = cwv[n][1], w2v = cwv[n][2], bvv = cwv[n][3], w0g = cwv[n][4], w1g = cwv[n][5], w2g = cwv[n][6], bvg = cwv[n][7];
; #pragma unroll
;             for (int ai = 0; ai < 2; ++ai) {
;                 if (n == 0 && ai == 0) {
;                     asm volatile("" ::: "memory");
;                     const float* cv = cw + hc0 + 4; const float* cg = cv + FH; const float* bp = cb + hc0 + 4;
;                     cwv[1][0] = *(const f32x4*)(cv); cwv[1][1] = *(const f32x4*)(cv + F2); cwv[1][2] = *(const f32x4*)(cv + 2 * F2); cwv[1][3] = *(const f32x4*)(bp);
;                     cwv[1][4] = *(const f32x4*)(cg); cwv[1][5] = *(const f32x4*)(cg + F2); cwv[1][6] = *(const f32x4*)(cg + 2 * F2); cwv[1][7] = *(const f32x4*)(bp + FH);
;                     asm volatile("" ::: "memory"); }
;                 f32x4 h2v = (f32x4){0.f, 0.f, 0.f, 0.f}, h3v = h2v, h2g = h2v, h3g = h2v;
;                 const int pb = ai * 2 + wr - 1;
;                 if (pb >= 0 && fr == 0) { const LAS float* xp = xch + (pb * 2) * 256 + clb + 4 * n;
;                     h2v = *(const LAS f32x4*)(xp); h3v = *(const LAS f32x4*)(xp + 256); h2g = *(const LAS f32x4*)(xp + 128); h3g = *(const LAS f32x4*)(xp + 256 + 128); }
;                 float o[4][4];
; #pragma unroll
;                 for (int j = 0; j < 4; ++j) {
;                     const float v0 = acc[ai][0][0][n][j], v1 = acc[ai][0][1][n][j], v2 = acc[ai][0][2][n][j], v3 = acc[ai][0][3][n][j];
;                     const float g0 = acc[ai][1][0][n][j], g1 = acc[ai][1][1][n][j], g2 = acc[ai][1][2][n][j], g3 = acc[ai][1][3][n][j];
;                     const float pv3 = dpp_upd<0x111>(h3v[j], v3), pv2 = dpp_upd<0x111>(h2v[j], v2), pg3 = dpp_upd<0x111>(h3g[j], g3), pg2 = dpp_upd<0x111>(h2g[j], g2);
;                     const float hv0 = bvv[j] + w2v[j] * v0 + w1v[j] * pv3 + w0v[j] * pv2, hv1 = bvv[j] + w2v[j] * v1 + w1v[j] * v0 + w0v[j] * pv3;
;                     const float hv2 = bvv[j] + w2v[j] * v2 + w1v[j] * v1 + w0v[j] * v0, hv3 = bvv[j] + w2v[j] * v3 + w1v[j] * v2 + w0v[j] * v1;
;                     const float hg0 = bvg[j] + w2g[j] * g0 + w1g[j] * pg3 + w0g[j] * pg2, hg1 = bvg[j] + w2g[j] * g1 + w1g[j] * g0 + w0g[j] * pg3;
.LBB0_322:
	s_or_b64 exec, exec, s[34:35]
	s_waitcnt lgkmcnt(0)
	v_mov_b32_dpp v70, v44 row_shr:1 row_mask:0xf bank_mask:0xf
	v_mov_b32_dpp v71, v45 row_shr:1 row_mask:0xf bank_mask:0xf
	s_waitcnt vmcnt(8)
	v_pk_fma_f32 v[84:85], v[56:57], v[120:121], v[124:125]
	v_mov_b32_dpp v78, v32 row_shr:1 row_mask:0xf bank_mask:0xf
	v_mov_b32_dpp v79, v33 row_shr:1 row_mask:0xf bank_mask:0xf
	v_pk_fma_f32 v[84:85], v[116:117], v[70:71], v[84:85]
	v_mov_b32_dpp v66, v52 row_shr:1 row_mask:0xf bank_mask:0xf
	v_pk_fma_f32 v[78:79], v[112:113], v[78:79], v[84:85]
	v_mov_b32_dpp v67, v53 row_shr:1 row_mask:0xf bank_mask:0xf
	v_mul_f32_e32 v65, 0xbfb8aa3b, v78
	v_exp_f32_e32 v65, v65
	v_mul_f32_e32 v84, 0xbfb8aa3b, v79
	v_exp_f32_e32 v85, v84
	v_pk_fma_f32 v[86:87], v[60:61], v[104:105], v[108:109]
	v_add_f32_e32 v65, 1.0, v65
	v_rcp_f32_e32 v84, v65
	v_add_f32_e32 v65, 1.0, v85
	v_rcp_f32_e32 v85, v65
	v_mov_b32_dpp v74, v40 row_shr:1 row_mask:0xf bank_mask:0xf
	v_mov_b32_dpp v75, v41 row_shr:1 row_mask:0xf bank_mask:0xf
	v_pk_fma_f32 v[86:87], v[100:101], v[66:67], v[86:87]
	v_pk_mul_f32 v[78:79], v[78:79], v[84:85]
	v_pk_fma_f32 v[74:75], v[96:97], v[74:75], v[86:87]
	v_mov_b32_dpp v72, v46 row_shr:1 row_mask:0xf bank_mask:0xf
	v_mov_b32_dpp v73, v47 row_shr:1 row_mask:0xf bank_mask:0xf
	v_pk_mul_f32 v[74:75], v[74:75], v[78:79]
	v_pk_fma_f32 v[78:79], v[58:59], v[122:123], v[126:127]
	v_mov_b32_dpp v80, v34 row_shr:1 row_mask:0xf bank_mask:0xf
	v_mov_b32_dpp v81, v35 row_shr:1 row_mask:0xf bank_mask:0xf
	v_pk_fma_f32 v[78:79], v[118:119], v[72:73], v[78:79]
	v_mov_b32_dpp v68, v54 row_shr:1 row_mask:0xf bank_mask:0xf
	v_pk_fma_f32 v[78:79], v[114:115], v[80:81], v[78:79]
	v_mov_b32_dpp v69, v55 row_shr:1 row_mask:0xf bank_mask:0xf
	v_mul_f32_e32 v65, 0xbfb8aa3b, v78
	v_exp_f32_e32 v65, v65
	v_mul_f32_e32 v80, 0xbfb8aa3b, v79
	v_exp_f32_e32 v81, v80
	v_pk_fma_f32 v[84:85], v[62:63], v[106:107], v[110:111]
	v_add_f32_e32 v65, 1.0, v65
	v_rcp_f32_e32 v80, v65
	v_add_f32_e32 v65, 1.0, v81
	v_rcp_f32_e32 v81, v65
	v_mov_b32_dpp v76, v42 row_shr:1 row_mask:0xf bank_mask:0xf
	v_mov_b32_dpp v77, v43 row_shr:1 row_mask:0xf bank_mask:0xf
	v_pk_fma_f32 v[84:85], v[102:103], v[68:69], v[84:85]
	v_pk_mul_f32 v[78:79], v[78:79], v[80:81]
	v_pk_fma_f32 v[76:77], v[98:99], v[76:77], v[84:85]
	v_cvt_pk_bf16_f32 v74, v74, v75
	v_pk_mul_f32 v[76:77], v[76:77], v[78:79]
	v_pk_fma_f32 v[44:45], v[44:45], v[120:121], v[124:125]
	v_cvt_pk_bf16_f32 v75, v76, v77
	v_pk_fma_f32 v[76:77], v[36:37], v[120:121], v[124:125]
	global_store_dwordx2 v[202:203], v[74:75], off offset:8
	v_pk_fma_f32 v[76:77], v[56:57], v[116:117], v[76:77]
	v_pk_fma_f32 v[52:53], v[52:53], v[104:105], v[108:109]
	v_pk_fma_f32 v[70:71], v[112:113], v[70:71], v[76:77]
	s_nop 0
	v_mul_f32_e32 v65, 0xbfb8aa3b, v70
	v_exp_f32_e32 v65, v65
	v_mul_f32_e32 v76, 0xbfb8aa3b, v71
	v_exp_f32_e32 v76, v76
	v_add_f32_e32 v65, 1.0, v65
	v_rcp_f32_e32 v74, v65
	v_add_f32_e32 v65, 1.0, v76
	v_rcp_f32_e32 v75, v65
	v_pk_fma_f32 v[76:77], v[48:49], v[104:105], v[108:109]
	v_pk_mul_f32 v[70:71], v[70:71], v[74:75]
	v_pk_fma_f32 v[76:77], v[60:61], v[100:101], v[76:77]
	v_pk_fma_f32 v[74:75], v[50:51], v[106:107], v[110:111]
	v_pk_fma_f32 v[66:67], v[96:97], v[66:67], v[76:77]
	v_pk_fma_f32 v[74:75], v[62:63], v[102:103], v[74:75]
	v_pk_mul_f32 v[66:67], v[66:67], v[70:71]
	v_pk_fma_f32 v[70:71], v[38:39], v[122:123], v[126:127]
	v_pk_fma_f32 v[68:69], v[98:99], v[68:69], v[74:75]
	v_pk_fma_f32 v[70:71], v[58:59], v[118:119], v[70:71]
	v_cvt_pk_bf16_f32 v66, v66, v67
	v_pk_fma_f32 v[70:71], v[114:115], v[72:73], v[70:71]
	s_nop 0
	v_mul_f32_e32 v65, 0xbfb8aa3b, v70
	v_exp_f32_e32 v65, v65
; #define LAS __attribute__((address_space(3)))
; __device__ __forceinline__ float sigmoidf_(float x) { return __builtin_amdgcn_rcpf(1.0f + __expf(-x)); }
;     __device__ __forceinline__ void operator()(AccRef acc, const Unit& u, int wr, int wc, int fr, int fq) const {
;     ...
;                 f32x4 h2v = (f32x4){0.f, 0.f, 0.f, 0.f}, h3v = h2v, h2g = h2v, h3g = h2v;
;                 const int pb = ai * 2 + wr - 1;
;                 if (pb >= 0 && fr == 0) { const LAS float* xp = xch + (pb * 2) * 256 + clb + 4 * n;
;                     h2v = *(const LAS f32x4*)(xp); h3v = *(const LAS f32x4*)(xp + 256); h2g = *(const LAS f32x4*)(xp + 128); h3g = *(const LAS f32x4*)(xp + 256 + 128); }
;     ...
;                 for (int j = 0; j < 4; ++j) {
;                     const float v0 = acc[ai][0][0][n][j], v1 = acc[ai][0][1][n][j], v2 = acc[ai][0][2][n][j], v3 = acc[ai][0][3][n][j];
;                     const float g0 = acc[ai][1][0][n][j], g1 = acc[ai][1][1][n][j], g2 = acc[ai][1][2][n][j], g3 = acc[ai][1][3][n][j];
;                     const float pv3 = dpp_upd<0x111>(h3v[j], v3), pv2 = dpp_upd<0x111>(h2v[j], v2), pg3 = dpp_upd<0x111>(h3g[j], g3), pg2 = dpp_upd<0x111>(h2g[j], g2);
;                     const float hv0 = bvv[j] + w2v[j] * v0 + w1v[j] * pv3 + w0v[j] * pv2, hv1 = bvv[j] + w2v[j] * v1 + w1v[j] * v0 + w0v[j] * pv3;
;                     const float hv2 = bvv[j] + w2v[j] * v2 + w1v[j] * v1 + w0v[j] * v0, hv3 = bvv[j] + w2v[j] * v3 + w1v[j] * v2 + w0v[j] * v1;
;                     const float hg0 = bvg[j] + w2g[j] * g0 + w1g[j] * pg3 + w0g[j] * pg2, hg1 = bvg[j] + w2g[j] * g1 + w1g[j] * g0 + w0g[j] * pg3;
;                     const float hg2 = bvg[j] + w2g[j] * g2 + w1g[j] * g1 + w0g[j] * g0, hg3 = bvg[j] + w2g[j] * g3 + w1g[j] * g2 + w0g[j] * g1;
;                     o[0][j] = hg0 * sigmoidf_(hg0) * hv0; o[1][j] = hg1 * sigmoidf_(hg1) * hv1; o[2][j] = hg2 * sigmoidf_(hg2) * hv2; o[3][j] = hg3 * sigmoidf_(hg3) * hv3; }
; #pragma unroll
;                 for (int m = 0; m < 4; ++m) { u32x2 w; w.x = cvt_pk_bf16(o[m][0], o[m][1]); w.y = cvt_pk_bf16(o[m][2], o[m][3]);
;                     *(u32x2*)(Aout + (size_t)(row0 + ai * 128 + m) * FH + hc0 + 4 * n) = w; } } }
	v_mul_f32_e32 v72, 0xbfb8aa3b, v71
	v_exp_f32_e32 v73, v72
	v_add_f32_e32 v65, 1.0, v65
	v_rcp_f32_e32 v72, v65
	v_add_f32_e32 v65, 1.0, v73
	v_rcp_f32_e32 v73, v65
	s_nop 0
	v_pk_mul_f32 v[70:71], v[70:71], v[72:73]
	s_nop 0
	v_pk_mul_f32 v[68:69], v[68:69], v[70:71]
	s_nop 0
	v_cvt_pk_bf16_f32 v67, v68, v69
	v_pk_fma_f32 v[68:69], v[32:33], v[120:121], v[124:125]
	global_store_dwordx2 v[196:197], v[66:67], off offset:8
	v_pk_fma_f32 v[68:69], v[36:37], v[116:117], v[68:69]
	v_pk_fma_f32 v[32:33], v[32:33], v[116:117], v[44:45]
	v_pk_fma_f32 v[56:57], v[56:57], v[112:113], v[68:69]
	v_pk_fma_f32 v[32:33], v[36:37], v[112:113], v[32:33]
	v_mul_f32_e32 v65, 0xbfb8aa3b, v56
	v_exp_f32_e32 v65, v65
	v_mul_f32_e32 v68, 0xbfb8aa3b, v57
	v_exp_f32_e32 v68, v68
	v_mul_f32_e32 v36, 0xbfb8aa3b, v32
	v_add_f32_e32 v65, 1.0, v65
	v_rcp_f32_e32 v66, v65
	v_add_f32_e32 v65, 1.0, v68
	v_rcp_f32_e32 v67, v65
	v_pk_fma_f32 v[68:69], v[40:41], v[104:105], v[108:109]
	v_exp_f32_e32 v44, v36
	v_pk_fma_f32 v[68:69], v[48:49], v[100:101], v[68:69]
	v_pk_mul_f32 v[56:57], v[56:57], v[66:67]
	v_pk_fma_f32 v[60:61], v[60:61], v[96:97], v[68:69]
	v_pk_fma_f32 v[36:37], v[46:47], v[122:123], v[126:127]
	v_pk_mul_f32 v[56:57], v[60:61], v[56:57]
	v_pk_fma_f32 v[60:61], v[34:35], v[122:123], v[126:127]
	v_pk_fma_f32 v[34:35], v[34:35], v[118:119], v[36:37]
	v_pk_fma_f32 v[60:61], v[38:39], v[118:119], v[60:61]
	v_pk_fma_f32 v[34:35], v[38:39], v[114:115], v[34:35]
	v_pk_fma_f32 v[58:59], v[58:59], v[114:115], v[60:61]
	v_mul_f32_e32 v45, 0xbfb8aa3b, v33
	v_mul_f32_e32 v60, 0xbfb8aa3b, v58
	v_mul_f32_e32 v36, 0xbfb8aa3b, v34
	v_mul_f32_e32 v37, 0xbfb8aa3b, v35
	v_exp_f32_e32 v60, v60
	v_mul_f32_e32 v61, 0xbfb8aa3b, v59
	v_exp_f32_e32 v45, v45
	v_exp_f32_e32 v36, v36
	v_exp_f32_e32 v37, v37
	v_exp_f32_e32 v61, v61
	v_cvt_pk_bf16_f32 v56, v56, v57
	v_add_f32_e32 v57, 1.0, v60
	v_add_f32_e32 v44, 1.0, v44
	v_add_f32_e32 v45, 1.0, v45
	v_add_f32_e32 v36, 1.0, v36
	v_add_f32_e32 v37, 1.0, v37
	v_rcp_f32_e32 v60, v57
	v_add_f32_e32 v57, 1.0, v61
	v_rcp_f32_e32 v44, v44
	v_rcp_f32_e32 v45, v45
	v_rcp_f32_e32 v36, v36
	v_rcp_f32_e32 v37, v37
	v_rcp_f32_e32 v61, v57
	v_pk_fma_f32 v[46:47], v[54:55], v[106:107], v[110:111]
	v_pk_fma_f32 v[66:67], v[42:43], v[106:107], v[110:111]
	v_pk_fma_f32 v[40:41], v[40:41], v[100:101], v[52:53]
	v_pk_fma_f32 v[38:39], v[42:43], v[102:103], v[46:47]
	v_pk_fma_f32 v[66:67], v[50:51], v[102:103], v[66:67]
	v_pk_fma_f32 v[40:41], v[48:49], v[96:97], v[40:41]
	v_pk_mul_f32 v[32:33], v[32:33], v[44:45]
	v_pk_fma_f32 v[38:39], v[50:51], v[98:99], v[38:39]
	v_pk_mul_f32 v[34:35], v[34:35], v[36:37]
	v_pk_fma_f32 v[62:63], v[62:63], v[98:99], v[66:67]
	v_pk_mul_f32 v[58:59], v[58:59], v[60:61]
	v_pk_mul_f32 v[32:33], v[40:41], v[32:33]
	v_pk_mul_f32 v[34:35], v[38:39], v[34:35]
	v_pk_mul_f32 v[58:59], v[62:63], v[58:59]
	v_cvt_pk_bf16_f32 v32, v32, v33
	v_cvt_pk_bf16_f32 v33, v34, v35
	v_cvt_pk_bf16_f32 v57, v58, v59
	global_store_dwordx2 v[140:141], v[32:33], off offset:8
	v_mov_b32_e32 v65, 0
	v_mov_b32_e32 v66, 0
	v_mov_b32_e32 v67, 0
	v_mov_b32_e32 v40, 0
	v_mov_b32_e32 v41, 0
	v_mov_b32_e32 v42, 0
	v_mov_b32_e32 v43, 0
	v_mov_b32_e32 v32, 0
	v_mov_b32_e32 v33, 0
	v_mov_b32_e32 v34, 0
	v_mov_b32_e32 v35, 0
	v_mov_b32_e32 v36, 0
	v_mov_b32_e32 v37, 0
	v_mov_b32_e32 v38, 0
	v_mov_b32_e32 v39, 0
	global_store_dwordx2 v[152:153], v[56:57], off offset:8
	s_and_saveexec_b64 s[34:35], s[22:23]
	s_cbranch_execz .LBB0_305
	ds_read_b128 v[36:39], v237 offset:2064
	ds_read_b128 v[40:43], v237 offset:2576
	ds_read_b128 v[32:35], v237 offset:3088
	ds_read_b128 v[64:67], v237 offset:3600
	s_branch .LBB0_305

; #define LAS __attribute__((address_space(3)))
; __device__ __forceinline__ float sigmoidf_(float x) { return __builtin_amdgcn_rcpf(1.0f + __expf(-x)); }
;     __device__ __forceinline__ void operator()(AccRef acc, const Unit& u, int wr, int wc, int fr, int fq) const {
;     ...
;                 f32x4 h2v = (f32x4){0.f, 0.f, 0.f, 0.f}, h3v = h2v, h2g = h2v, h3g = h2v;
;                 const int pb = ai * 2 + wr - 1;
;                 if (pb >= 0 && fr == 0) { const LAS float* xp = xch + (pb * 2) * 256 + clb + 4 * n;
;                     h2v = *(const LAS f32x4*)(xp); h3v = *(const LAS f32x4*)(xp + 256); h2g = *(const LAS f32x4*)(xp + 128); h3g = *(const LAS f32x4*)(xp + 256 + 128); }
;                 float o[4][4];
; #pragma unroll
;                 for (int j = 0; j < 4; ++j) {
;                     const float v0 = acc[ai][0][0][n][j], v1 = acc[ai][0][1][n][j], v2 = acc[ai][0][2][n][j], v3 = acc[ai][0][3][n][j];
;                     const float g0 = acc[ai][1][0][n][j], g1 = acc[ai][1][1][n][j], g2 = acc[ai][1][2][n][j], g3 = acc[ai][1][3][n][j];
;                     const float pv3 = dpp_upd<0x111>(h3v[j], v3), pv2 = dpp_upd<0x111>(h2v[j], v2), pg3 = dpp_upd<0x111>(h3g[j], g3), pg2 = dpp_upd<0x111>(h2g[j], g2);
;                     const float hv0 = bvv[j] + w2v[j] * v0 + w1v[j] * pv3 + w0v[j] * pv2, hv1 = bvv[j] + w2v[j] * v1 + w1v[j] * v0 + w0v[j] * pv3;
;                     const float hv2 = bvv[j] + w2v[j] * v2 + w1v[j] * v1 + w0v[j] * v0, hv3 = bvv[j] + w2v[j] * v3 + w1v[j] * v2 + w0v[j] * v1;
;                     const float hg0 = bvg[j] + w2g[j] * g0 + w1g[j] * pg3 + w0g[j] * pg2, hg1 = bvg[j] + w2g[j] * g1 + w1g[j] * g0 + w0g[j] * pg3;
;                     const float hg2 = bvg[j] + w2g[j] * g2 + w1g[j] * g1 + w0g[j] * g0, hg3 = bvg[j] + w2g[j] * g3 + w1g[j] * g2 + w0g[j] * g1;
;                     o[0][j] = hg0 * sigmoidf_(hg0) * hv0; o[1][j] = hg1 * sigmoidf_(hg1) * hv1; o[2][j] = hg2 * sigmoidf_(hg2) * hv2; o[3][j] = hg3 * sigmoidf_(hg3) * hv3; }
; #pragma unroll
;                 for (int m = 0; m < 4; ++m) { u32x2 w; w.x = cvt_pk_bf16(o[m][0], o[m][1]); w.y = cvt_pk_bf16(o[m][2], o[m][3]);
;                     *(u32x2*)(Aout + (size_t)(row0 + ai * 128 + m) * FH + hc0 + 4 * n) = w; } } }
.LBB0_767:
	s_or_b64 exec, exec, s[42:43]
	s_waitcnt lgkmcnt(0)
	v_mov_b32_dpp v198, v140 row_shr:1 row_mask:0xf bank_mask:0xf
	v_mov_b32_dpp v199, v141 row_shr:1 row_mask:0xf bank_mask:0xf
	s_waitcnt vmcnt(8)
	v_pk_fma_f32 v[248:249], v[152:153], v[184:185], v[188:189]
	v_mov_b32_dpp v206, v128 row_shr:1 row_mask:0xf bank_mask:0xf
	v_mov_b32_dpp v207, v129 row_shr:1 row_mask:0xf bank_mask:0xf
	v_pk_fma_f32 v[248:249], v[180:181], v[198:199], v[248:249]
	v_mov_b32_dpp v194, v148 row_shr:1 row_mask:0xf bank_mask:0xf
	v_pk_fma_f32 v[206:207], v[176:177], v[206:207], v[248:249]
	v_mov_b32_dpp v195, v149 row_shr:1 row_mask:0xf bank_mask:0xf
	v_mul_f32_e32 v193, 0xbfb8aa3b, v206
	v_exp_f32_e32 v193, v193
	v_mul_f32_e32 v247, 0xbfb8aa3b, v207
	v_exp_f32_e32 v247, v247
	v_pk_fma_f32 v[250:251], v[156:157], v[168:169], v[172:173]
	v_add_f32_e32 v193, 1.0, v193
	v_rcp_f32_e32 v248, v193
	v_add_f32_e32 v193, 1.0, v247
	v_rcp_f32_e32 v249, v193
	v_mov_b32_dpp v202, v136 row_shr:1 row_mask:0xf bank_mask:0xf
	v_mov_b32_dpp v203, v137 row_shr:1 row_mask:0xf bank_mask:0xf
	v_pk_fma_f32 v[250:251], v[164:165], v[194:195], v[250:251]
	v_pk_mul_f32 v[206:207], v[206:207], v[248:249]
	v_pk_fma_f32 v[202:203], v[160:161], v[202:203], v[250:251]
	v_mov_b32_dpp v200, v142 row_shr:1 row_mask:0xf bank_mask:0xf
	v_mov_b32_dpp v201, v143 row_shr:1 row_mask:0xf bank_mask:0xf
	v_pk_mul_f32 v[202:203], v[202:203], v[206:207]
	v_pk_fma_f32 v[206:207], v[154:155], v[186:187], v[190:191]
	v_mov_b32_dpp v208, v130 row_shr:1 row_mask:0xf bank_mask:0xf
	v_mov_b32_dpp v209, v131 row_shr:1 row_mask:0xf bank_mask:0xf
	v_pk_fma_f32 v[206:207], v[182:183], v[200:201], v[206:207]
	v_mov_b32_dpp v196, v150 row_shr:1 row_mask:0xf bank_mask:0xf
	v_pk_fma_f32 v[206:207], v[178:179], v[208:209], v[206:207]
	v_mov_b32_dpp v197, v151 row_shr:1 row_mask:0xf bank_mask:0xf
	v_mul_f32_e32 v193, 0xbfb8aa3b, v206
	v_exp_f32_e32 v193, v193
	v_mul_f32_e32 v208, 0xbfb8aa3b, v207
	v_exp_f32_e32 v209, v208
	v_cvt_pk_bf16_f32 v208, v202, v203
	v_add_f32_e32 v193, 1.0, v193
	v_rcp_f32_e32 v202, v193
	v_add_f32_e32 v193, 1.0, v209
	v_rcp_f32_e32 v203, v193
	v_pk_fma_f32 v[248:249], v[158:159], v[170:171], v[174:175]
	v_mov_b32_dpp v204, v138 row_shr:1 row_mask:0xf bank_mask:0xf
	v_mov_b32_dpp v205, v139 row_shr:1 row_mask:0xf bank_mask:0xf
	v_pk_fma_f32 v[248:249], v[166:167], v[196:197], v[248:249]
	v_pk_mul_f32 v[202:203], v[206:207], v[202:203]
	v_pk_fma_f32 v[204:205], v[162:163], v[204:205], v[248:249]
	v_lshl_add_u32 v246, s40, 8, v236
	v_pk_mul_f32 v[202:203], v[204:205], v[202:203]
	v_lshlrev_b64 v[204:205], 1, v[232:233]
	v_pk_fma_f32 v[232:233], v[132:133], v[184:185], v[188:189]
	v_mov_b64_e32 v[206:207], s[60:61]
	v_pk_fma_f32 v[232:233], v[152:153], v[180:181], v[232:233]
	v_cvt_pk_bf16_f32 v209, v202, v203
	v_pk_fma_f32 v[198:199], v[176:177], v[198:199], v[232:233]
	v_mad_i64_i32 v[202:203], s[40:41], v246, s76, v[206:207]
	v_mul_f32_e32 v193, 0xbfb8aa3b, v198
	v_exp_f32_e32 v193, v193
	v_mul_f32_e32 v232, 0xbfb8aa3b, v199
	v_exp_f32_e32 v232, v232
	v_lshl_add_u64 v[202:203], v[202:203], 0, v[204:205]
	v_add_f32_e32 v193, 1.0, v193
	global_store_dwordx2 v[202:203], v[208:209], off
	v_rcp_f32_e32 v208, v193
	v_add_f32_e32 v193, 1.0, v232
	v_rcp_f32_e32 v209, v193
	v_pk_fma_f32 v[232:233], v[144:145], v[168:169], v[172:173]
	v_pk_fma_f32 v[140:141], v[140:141], v[184:185], v[188:189]
	v_pk_fma_f32 v[232:233], v[156:157], v[164:165], v[232:233]
	v_pk_mul_f32 v[198:199], v[198:199], v[208:209]
	v_pk_fma_f32 v[194:195], v[160:161], v[194:195], v[232:233]
	v_pk_fma_f32 v[208:209], v[146:147], v[170:171], v[174:175]
	v_pk_mul_f32 v[194:195], v[194:195], v[198:199]
	v_pk_fma_f32 v[198:199], v[134:135], v[186:187], v[190:191]
	v_pk_fma_f32 v[208:209], v[158:159], v[166:167], v[208:209]
	v_pk_fma_f32 v[198:199], v[154:155], v[182:183], v[198:199]
	v_pk_fma_f32 v[196:197], v[162:163], v[196:197], v[208:209]
	v_pk_fma_f32 v[198:199], v[178:179], v[200:201], v[198:199]
	v_cvt_pk_bf16_f32 v194, v194, v195
	v_mul_f32_e32 v193, 0xbfb8aa3b, v198
	v_exp_f32_e32 v193, v193
	v_mul_f32_e32 v200, 0xbfb8aa3b, v199
	v_exp_f32_e32 v201, v200
	v_pk_fma_f32 v[148:149], v[148:149], v[168:169], v[172:173]
	v_add_f32_e32 v193, 1.0, v193
; #define LAS __attribute__((address_space(3)))
; __device__ __forceinline__ float sigmoidf_(float x) { return __builtin_amdgcn_rcpf(1.0f + __expf(-x)); }
;     __device__ __forceinline__ void operator()(AccRef acc, const Unit& u, int wr, int wc, int fr, int fq) const {
;     ...
;                 f32x4 h2v = (f32x4){0.f, 0.f, 0.f, 0.f}, h3v = h2v, h2g = h2v, h3g = h2v;
;                 const int pb = ai * 2 + wr - 1;
;                 if (pb >= 0 && fr == 0) { const LAS float* xp = xch + (pb * 2) * 256 + clb + 4 * n;
;                     h2v = *(const LAS f32x4*)(xp); h3v = *(const LAS f32x4*)(xp + 256); h2g = *(const LAS f32x4*)(xp + 128); h3g = *(const LAS f32x4*)(xp + 256 + 128); }
;     ...
;                     o[0][j] = hg0 * sigmoidf_(hg0) * hv0; o[1][j] = hg1 * sigmoidf_(hg1) * hv1; o[2][j] = hg2 * sigmoidf_(hg2) * hv2; o[3][j] = hg3 * sigmoidf_(hg3) * hv3; }
; #pragma unroll
;                 for (int m = 0; m < 4; ++m) { u32x2 w; w.x = cvt_pk_bf16(o[m][0], o[m][1]); w.y = cvt_pk_bf16(o[m][2], o[m][3]);
;                     *(u32x2*)(Aout + (size_t)(row0 + ai * 128 + m) * FH + hc0 + 4 * n) = w; } } }
	v_rcp_f32_e32 v200, v193
	v_add_f32_e32 v193, 1.0, v201
	v_rcp_f32_e32 v201, v193
	v_or_b32_e32 v193, 1, v246
	v_pk_mul_f32 v[198:199], v[198:199], v[200:201]
	s_nop 0
	v_pk_mul_f32 v[196:197], v[196:197], v[198:199]
	v_pk_fma_f32 v[198:199], v[128:129], v[184:185], v[188:189]
	v_cvt_pk_bf16_f32 v195, v196, v197
	v_pk_fma_f32 v[198:199], v[132:133], v[180:181], v[198:199]
	v_mad_i64_i32 v[196:197], s[40:41], v193, s76, v[206:207]
	v_pk_fma_f32 v[152:153], v[152:153], v[176:177], v[198:199]
	v_lshl_add_u64 v[196:197], v[196:197], 0, v[204:205]
	v_mul_f32_e32 v193, 0xbfb8aa3b, v152
	v_exp_f32_e32 v193, v193
	v_mul_f32_e32 v198, 0xbfb8aa3b, v153
	v_exp_f32_e32 v198, v198
	global_store_dwordx2 v[196:197], v[194:195], off
	v_add_f32_e32 v193, 1.0, v193
	v_rcp_f32_e32 v194, v193
	v_add_f32_e32 v193, 1.0, v198
	v_rcp_f32_e32 v195, v193
	v_pk_fma_f32 v[198:199], v[136:137], v[168:169], v[172:173]
	v_pk_fma_f32 v[128:129], v[128:129], v[180:181], v[140:141]
	v_pk_fma_f32 v[198:199], v[144:145], v[164:165], v[198:199]
	v_pk_fma_f32 v[128:129], v[132:133], v[176:177], v[128:129]
	v_pk_fma_f32 v[156:157], v[156:157], v[160:161], v[198:199]
	v_pk_mul_f32 v[152:153], v[152:153], v[194:195]
	v_mul_f32_e32 v132, 0xbfb8aa3b, v128
	v_pk_mul_f32 v[152:153], v[156:157], v[152:153]
	v_pk_fma_f32 v[156:157], v[130:131], v[186:187], v[190:191]
	v_exp_f32_e32 v140, v132
	v_pk_fma_f32 v[132:133], v[142:143], v[186:187], v[190:191]
	v_pk_fma_f32 v[156:157], v[134:135], v[182:183], v[156:157]
	v_pk_fma_f32 v[130:131], v[130:131], v[182:183], v[132:133]
	v_pk_fma_f32 v[154:155], v[154:155], v[178:179], v[156:157]
	v_pk_fma_f32 v[130:131], v[134:135], v[178:179], v[130:131]
	v_mul_f32_e32 v156, 0xbfb8aa3b, v154
	v_mul_f32_e32 v141, 0xbfb8aa3b, v129
	v_mul_f32_e32 v132, 0xbfb8aa3b, v130
	v_mul_f32_e32 v133, 0xbfb8aa3b, v131
	v_exp_f32_e32 v157, v156
	v_mul_f32_e32 v156, 0xbfb8aa3b, v155
	v_exp_f32_e32 v141, v141
	v_exp_f32_e32 v132, v132
	v_exp_f32_e32 v133, v133
	v_exp_f32_e32 v193, v156
	v_add_f32_e32 v140, 1.0, v140
	v_add_f32_e32 v141, 1.0, v141
	v_add_f32_e32 v132, 1.0, v132
	v_add_f32_e32 v133, 1.0, v133
	v_cvt_pk_bf16_f32 v156, v152, v153
	v_add_f32_e32 v152, 1.0, v157
	v_add_f32_e32 v153, 1.0, v193
	v_rcp_f32_e32 v140, v140
	v_rcp_f32_e32 v141, v141
	v_rcp_f32_e32 v132, v132
	v_rcp_f32_e32 v133, v133
	v_rcp_f32_e32 v152, v152
	v_rcp_f32_e32 v153, v153
	v_pk_fma_f32 v[142:143], v[150:151], v[170:171], v[174:175]
	v_pk_fma_f32 v[194:195], v[138:139], v[170:171], v[174:175]
	v_pk_fma_f32 v[136:137], v[136:137], v[164:165], v[148:149]
	v_pk_fma_f32 v[134:135], v[138:139], v[166:167], v[142:143]
	v_pk_fma_f32 v[194:195], v[146:147], v[166:167], v[194:195]
	v_pk_fma_f32 v[136:137], v[144:145], v[160:161], v[136:137]
	v_pk_mul_f32 v[128:129], v[128:129], v[140:141]
	v_pk_fma_f32 v[134:135], v[146:147], v[162:163], v[134:135]
	v_pk_mul_f32 v[130:131], v[130:131], v[132:133]
	v_pk_fma_f32 v[158:159], v[158:159], v[162:163], v[194:195]
	v_pk_mul_f32 v[152:153], v[154:155], v[152:153]
	v_pk_mul_f32 v[128:129], v[136:137], v[128:129]
	v_pk_mul_f32 v[130:131], v[134:135], v[130:131]
	v_pk_mul_f32 v[152:153], v[158:159], v[152:153]
	v_cvt_pk_bf16_f32 v128, v128, v129
	v_cvt_pk_bf16_f32 v129, v130, v131
	v_or_b32_e32 v130, 3, v246
	v_cvt_pk_bf16_f32 v157, v152, v153
	v_or_b32_e32 v152, 2, v246
	v_mad_i64_i32 v[130:131], s[40:41], v130, s76, v[206:207]
	v_mad_i64_i32 v[152:153], s[40:41], v152, s76, v[206:207]
	v_lshl_add_u64 v[140:141], v[130:131], 0, v[204:205]
	v_lshl_add_u64 v[152:153], v[152:153], 0, v[204:205]
	global_store_dwordx2 v[140:141], v[128:129], off
	v_mov_b32_e32 v193, 0
	v_mov_b32_e32 v194, 0
	v_mov_b32_e32 v195, 0
	v_mov_b32_e32 v136, 0
	v_mov_b32_e32 v137, 0
	v_mov_b32_e32 v138, 0
	v_mov_b32_e32 v139, 0
	v_mov_b32_e32 v128, 0
	v_mov_b32_e32 v129, 0
	v_mov_b32_e32 v130, 0
	v_mov_b32_e32 v131, 0
	v_mov_b32_e32 v132, 0
	v_mov_b32_e32 v133, 0
	v_mov_b32_e32 v134, 0
	v_mov_b32_e32 v135, 0
	global_store_dwordx2 v[152:153], v[156:157], off
	s_and_saveexec_b64 s[40:41], s[28:29]
	s_cbranch_execz .LBB0_769
	ds_read_b128 v[132:135], v237 offset:2048
	ds_read_b128 v[136:139], v237 offset:2560
	ds_read_b128 v[128:131], v237 offset:3072
	ds_read_b128 v[192:195], v237 offset:3584

;     __device__ __forceinline__ void operator()(AccRef acc, const Unit& u, int wr, int wc, int fr, int fq) const {
;     ...
;         for (int n = 0; n < 2; ++n) {
;             const f32x4 w0v = cwv[n][0], w1v = cwv[n][1], w2v = cwv[n][2], bvv = cwv[n][3], w0g = cwv[n][4], w1g = cwv[n][5], w2g = cwv[n][6], bvg = cwv[n][7];
; #pragma unroll
;             for (int ai = 0; ai < 2; ++ai) {
;                 if (n == 0 && ai == 0) {
;                     asm volatile("" ::: "memory");
;                     const float* cv = cw + hc0 + 4; const float* cg = cv + FH; const float* bp = cb + hc0 + 4;
;                     cwv[1][0] = *(const f32x4*)(cv); cwv[1][1] = *(const f32x4*)(cv + F2); cwv[1][2] = *(const f32x4*)(cv + 2 * F2); cwv[1][3] = *(const f32x4*)(bp);
;                     cwv[1][4] = *(const f32x4*)(cg); cwv[1][5] = *(const f32x4*)(cg + F2); cwv[1][6] = *(const f32x4*)(cg + 2 * F2); cwv[1][7] = *(const f32x4*)(bp + FH);
;                     asm volatile("" ::: "memory"); }
;                 f32x4 h2v = (f32x4){0.f, 0.f, 0.f, 0.f}, h3v = h2v, h2g = h2v, h3g = h2v;
;                 const int pb = ai * 2 + wr - 1;
;                 if (pb >= 0 && fr == 0) { const LAS float* xp = xch + (pb * 2) * 256 + clb + 4 * n;
;                     h2v = *(const LAS f32x4*)(xp); h3v = *(const LAS f32x4*)(xp + 256); h2g = *(const LAS f32x4*)(xp + 128); h3g = *(const LAS f32x4*)(xp + 256 + 128); }
;                 float o[4][4];
; #pragma unroll
;                 for (int j = 0; j < 4; ++j) {
;                     const float v0 = acc[ai][0][0][n][j], v1 = acc[ai][0][1][n][j], v2 = acc[ai][0][2][n][j], v3 = acc[ai][0][3][n][j];
;                     const float g0 = acc[ai][1][0][n][j], g1 = acc[ai][1][1][n][j], g2 = acc[ai][1][2][n][j], g3 = acc[ai][1][3][n][j];
;                     const float pv3 = dpp_upd<0x111>(h3v[j], v3), pv2 = dpp_upd<0x111>(h2v[j], v2), pg3 = dpp_upd<0x111>(h3g[j], g3), pg2 = dpp_upd<0x111>(h2g[j], g2);
;                     const float hv0 = bvv[j] + w2v[j] * v0 + w1v[j] * pv3 + w0v[j] * pv2, hv1 = bvv[j] + w2v[j] * v1 + w1v[j] * v0 + w0v[j] * pv3;
;                     const float hv2 = bvv[j] + w2v[j] * v2 + w1v[j] * v1 + w0v[j] * v0, hv3 = bvv[j] + w2v[j] * v3 + w1v[j] * v2 + w0v[j] * v1;
;                     const float hg0 = bvg[j] + w2g[j] * g0 + w1g[j] * pg3 + w0g[j] * pg2, hg1 = bvg[j] + w2g[j] * g1 + w1g[j] * g0 + w0g[j] * pg3;
.LBB0_771:
	s_or_b64 exec, exec, s[40:41]
	s_waitcnt lgkmcnt(0)
	v_mov_b32_dpp v70, v44 row_shr:1 row_mask:0xf bank_mask:0xf
	v_mov_b32_dpp v71, v45 row_shr:1 row_mask:0xf bank_mask:0xf
	s_waitcnt vmcnt(8)
	v_pk_fma_f32 v[84:85], v[56:57], v[120:121], v[124:125]
	v_mov_b32_dpp v78, v32 row_shr:1 row_mask:0xf bank_mask:0xf
	v_mov_b32_dpp v79, v33 row_shr:1 row_mask:0xf bank_mask:0xf
	v_pk_fma_f32 v[84:85], v[116:117], v[70:71], v[84:85]
	v_mov_b32_dpp v66, v52 row_shr:1 row_mask:0xf bank_mask:0xf
	v_pk_fma_f32 v[78:79], v[112:113], v[78:79], v[84:85]
	v_mov_b32_dpp v67, v53 row_shr:1 row_mask:0xf bank_mask:0xf
	v_mul_f32_e32 v65, 0xbfb8aa3b, v78
	v_exp_f32_e32 v65, v65
	v_mul_f32_e32 v84, 0xbfb8aa3b, v79
	v_exp_f32_e32 v85, v84
	v_pk_fma_f32 v[86:87], v[60:61], v[104:105], v[108:109]
	v_add_f32_e32 v65, 1.0, v65
	v_rcp_f32_e32 v84, v65
	v_add_f32_e32 v65, 1.0, v85
	v_rcp_f32_e32 v85, v65
	v_mov_b32_dpp v74, v40 row_shr:1 row_mask:0xf bank_mask:0xf
	v_mov_b32_dpp v75, v41 row_shr:1 row_mask:0xf bank_mask:0xf
	v_pk_fma_f32 v[86:87], v[100:101], v[66:67], v[86:87]
	v_pk_mul_f32 v[78:79], v[78:79], v[84:85]
	v_pk_fma_f32 v[74:75], v[96:97], v[74:75], v[86:87]
	v_mov_b32_dpp v72, v46 row_shr:1 row_mask:0xf bank_mask:0xf
	v_mov_b32_dpp v73, v47 row_shr:1 row_mask:0xf bank_mask:0xf
	v_pk_mul_f32 v[74:75], v[74:75], v[78:79]
	v_pk_fma_f32 v[78:79], v[58:59], v[122:123], v[126:127]
	v_mov_b32_dpp v80, v34 row_shr:1 row_mask:0xf bank_mask:0xf
	v_mov_b32_dpp v81, v35 row_shr:1 row_mask:0xf bank_mask:0xf
	v_pk_fma_f32 v[78:79], v[118:119], v[72:73], v[78:79]
	v_mov_b32_dpp v68, v54 row_shr:1 row_mask:0xf bank_mask:0xf
	v_pk_fma_f32 v[78:79], v[114:115], v[80:81], v[78:79]
	v_mov_b32_dpp v69, v55 row_shr:1 row_mask:0xf bank_mask:0xf
	v_mul_f32_e32 v65, 0xbfb8aa3b, v78
	v_exp_f32_e32 v65, v65
	v_mul_f32_e32 v80, 0xbfb8aa3b, v79
	v_exp_f32_e32 v81, v80
	v_pk_fma_f32 v[84:85], v[62:63], v[106:107], v[110:111]
	v_add_f32_e32 v65, 1.0, v65
	v_rcp_f32_e32 v80, v65
	v_add_f32_e32 v65, 1.0, v81
	v_rcp_f32_e32 v81, v65
	v_mov_b32_dpp v76, v42 row_shr:1 row_mask:0xf bank_mask:0xf
	v_mov_b32_dpp v77, v43 row_shr:1 row_mask:0xf bank_mask:0xf
	v_pk_fma_f32 v[84:85], v[102:103], v[68:69], v[84:85]
	v_pk_mul_f32 v[78:79], v[78:79], v[80:81]
	v_pk_fma_f32 v[76:77], v[98:99], v[76:77], v[84:85]
	v_cvt_pk_bf16_f32 v74, v74, v75
	v_pk_mul_f32 v[76:77], v[76:77], v[78:79]
	v_pk_fma_f32 v[44:45], v[44:45], v[120:121], v[124:125]
	v_cvt_pk_bf16_f32 v75, v76, v77
	v_pk_fma_f32 v[76:77], v[36:37], v[120:121], v[124:125]
	global_store_dwordx2 v[202:203], v[74:75], off offset:8
	v_pk_fma_f32 v[76:77], v[56:57], v[116:117], v[76:77]
	v_pk_fma_f32 v[52:53], v[52:53], v[104:105], v[108:109]
	v_pk_fma_f32 v[70:71], v[112:113], v[70:71], v[76:77]
	s_nop 0
	v_mul_f32_e32 v65, 0xbfb8aa3b, v70
	v_exp_f32_e32 v65, v65
	v_mul_f32_e32 v76, 0xbfb8aa3b, v71
	v_exp_f32_e32 v76, v76
	v_add_f32_e32 v65, 1.0, v65
	v_rcp_f32_e32 v74, v65
	v_add_f32_e32 v65, 1.0, v76
	v_rcp_f32_e32 v75, v65
	v_pk_fma_f32 v[76:77], v[48:49], v[104:105], v[108:109]
	v_pk_mul_f32 v[70:71], v[70:71], v[74:75]
	v_pk_fma_f32 v[76:77], v[60:61], v[100:101], v[76:77]
	v_pk_fma_f32 v[74:75], v[50:51], v[106:107], v[110:111]
	v_pk_fma_f32 v[66:67], v[96:97], v[66:67], v[76:77]
	v_pk_fma_f32 v[74:75], v[62:63], v[102:103], v[74:75]
	v_pk_mul_f32 v[66:67], v[66:67], v[70:71]
	v_pk_fma_f32 v[70:71], v[38:39], v[122:123], v[126:127]
	v_pk_fma_f32 v[68:69], v[98:99], v[68:69], v[74:75]
	v_pk_fma_f32 v[70:71], v[58:59], v[118:119], v[70:71]
	v_cvt_pk_bf16_f32 v66, v66, v67
	v_pk_fma_f32 v[70:71], v[114:115], v[72:73], v[70:71]
	s_nop 0
	v_mul_f32_e32 v65, 0xbfb8aa3b, v70
	v_exp_f32_e32 v65, v65
; #define LAS __attribute__((address_space(3)))
; __device__ __forceinline__ float sigmoidf_(float x) { return __builtin_amdgcn_rcpf(1.0f + __expf(-x)); }
;     __device__ __forceinline__ void operator()(AccRef acc, const Unit& u, int wr, int wc, int fr, int fq) const {
;     ...
;                 f32x4 h2v = (f32x4){0.f, 0.f, 0.f, 0.f}, h3v = h2v, h2g = h2v, h3g = h2v;
;                 const int pb = ai * 2 + wr - 1;
;                 if (pb >= 0 && fr == 0) { const LAS float* xp = xch + (pb * 2) * 256 + clb + 4 * n;
;                     h2v = *(const LAS f32x4*)(xp); h3v = *(const LAS f32x4*)(xp + 256); h2g = *(const LAS f32x4*)(xp + 128); h3g = *(const LAS f32x4*)(xp + 256 + 128); }
;     ...
;                 for (int j = 0; j < 4; ++j) {
;                     const float v0 = acc[ai][0][0][n][j], v1 = acc[ai][0][1][n][j], v2 = acc[ai][0][2][n][j], v3 = acc[ai][0][3][n][j];
;                     const float g0 = acc[ai][1][0][n][j], g1 = acc[ai][1][1][n][j], g2 = acc[ai][1][2][n][j], g3 = acc[ai][1][3][n][j];
;                     const float pv3 = dpp_upd<0x111>(h3v[j], v3), pv2 = dpp_upd<0x111>(h2v[j], v2), pg3 = dpp_upd<0x111>(h3g[j], g3), pg2 = dpp_upd<0x111>(h2g[j], g2);
;                     const float hv0 = bvv[j] + w2v[j] * v0 + w1v[j] * pv3 + w0v[j] * pv2, hv1 = bvv[j] + w2v[j] * v1 + w1v[j] * v0 + w0v[j] * pv3;
;                     const float hv2 = bvv[j] + w2v[j] * v2 + w1v[j] * v1 + w0v[j] * v0, hv3 = bvv[j] + w2v[j] * v3 + w1v[j] * v2 + w0v[j] * v1;
;                     const float hg0 = bvg[j] + w2g[j] * g0 + w1g[j] * pg3 + w0g[j] * pg2, hg1 = bvg[j] + w2g[j] * g1 + w1g[j] * g0 + w0g[j] * pg3;
;                     const float hg2 = bvg[j] + w2g[j] * g2 + w1g[j] * g1 + w0g[j] * g0, hg3 = bvg[j] + w2g[j] * g3 + w1g[j] * g2 + w0g[j] * g1;
;                     o[0][j] = hg0 * sigmoidf_(hg0) * hv0; o[1][j] = hg1 * sigmoidf_(hg1) * hv1; o[2][j] = hg2 * sigmoidf_(hg2) * hv2; o[3][j] = hg3 * sigmoidf_(hg3) * hv3; }
; #pragma unroll
;                 for (int m = 0; m < 4; ++m) { u32x2 w; w.x = cvt_pk_bf16(o[m][0], o[m][1]); w.y = cvt_pk_bf16(o[m][2], o[m][3]);
;                     *(u32x2*)(Aout + (size_t)(row0 + ai * 128 + m) * FH + hc0 + 4 * n) = w; } } }
	v_mul_f32_e32 v72, 0xbfb8aa3b, v71
	v_exp_f32_e32 v73, v72
	v_add_f32_e32 v65, 1.0, v65
	v_rcp_f32_e32 v72, v65
	v_add_f32_e32 v65, 1.0, v73
	v_rcp_f32_e32 v73, v65
	s_nop 0
	v_pk_mul_f32 v[70:71], v[70:71], v[72:73]
	s_nop 0
	v_pk_mul_f32 v[68:69], v[68:69], v[70:71]
	s_nop 0
	v_cvt_pk_bf16_f32 v67, v68, v69
	v_pk_fma_f32 v[68:69], v[32:33], v[120:121], v[124:125]
	global_store_dwordx2 v[196:197], v[66:67], off offset:8
	v_pk_fma_f32 v[68:69], v[36:37], v[116:117], v[68:69]
	v_pk_fma_f32 v[32:33], v[32:33], v[116:117], v[44:45]
	v_pk_fma_f32 v[56:57], v[56:57], v[112:113], v[68:69]
	v_pk_fma_f32 v[32:33], v[36:37], v[112:113], v[32:33]
	v_mul_f32_e32 v65, 0xbfb8aa3b, v56
	v_exp_f32_e32 v65, v65
	v_mul_f32_e32 v68, 0xbfb8aa3b, v57
	v_exp_f32_e32 v68, v68
	v_mul_f32_e32 v36, 0xbfb8aa3b, v32
	v_add_f32_e32 v65, 1.0, v65
	v_rcp_f32_e32 v66, v65
	v_add_f32_e32 v65, 1.0, v68
	v_rcp_f32_e32 v67, v65
	v_pk_fma_f32 v[68:69], v[40:41], v[104:105], v[108:109]
	v_exp_f32_e32 v44, v36
	v_pk_fma_f32 v[68:69], v[48:49], v[100:101], v[68:69]
	v_pk_mul_f32 v[56:57], v[56:57], v[66:67]
	v_pk_fma_f32 v[60:61], v[60:61], v[96:97], v[68:69]
	v_pk_fma_f32 v[36:37], v[46:47], v[122:123], v[126:127]
	v_pk_mul_f32 v[56:57], v[60:61], v[56:57]
	v_pk_fma_f32 v[60:61], v[34:35], v[122:123], v[126:127]
	v_pk_fma_f32 v[34:35], v[34:35], v[118:119], v[36:37]
	v_pk_fma_f32 v[60:61], v[38:39], v[118:119], v[60:61]
	v_pk_fma_f32 v[34:35], v[38:39], v[114:115], v[34:35]
	v_pk_fma_f32 v[58:59], v[58:59], v[114:115], v[60:61]
	v_mul_f32_e32 v45, 0xbfb8aa3b, v33
	v_mul_f32_e32 v60, 0xbfb8aa3b, v58
	v_mul_f32_e32 v36, 0xbfb8aa3b, v34
	v_mul_f32_e32 v37, 0xbfb8aa3b, v35
	v_exp_f32_e32 v60, v60
	v_mul_f32_e32 v61, 0xbfb8aa3b, v59
	v_exp_f32_e32 v45, v45
	v_exp_f32_e32 v36, v36
	v_exp_f32_e32 v37, v37
	v_exp_f32_e32 v61, v61
	v_cvt_pk_bf16_f32 v56, v56, v57
	v_add_f32_e32 v57, 1.0, v60
	v_add_f32_e32 v44, 1.0, v44
	v_add_f32_e32 v45, 1.0, v45
	v_add_f32_e32 v36, 1.0, v36
	v_add_f32_e32 v37, 1.0, v37
	v_rcp_f32_e32 v60, v57
	v_add_f32_e32 v57, 1.0, v61
	v_rcp_f32_e32 v44, v44
	v_rcp_f32_e32 v45, v45
	v_rcp_f32_e32 v36, v36
	v_rcp_f32_e32 v37, v37
	v_rcp_f32_e32 v61, v57
	v_pk_fma_f32 v[46:47], v[54:55], v[106:107], v[110:111]
	v_pk_fma_f32 v[66:67], v[42:43], v[106:107], v[110:111]
	v_pk_fma_f32 v[40:41], v[40:41], v[100:101], v[52:53]
	v_pk_fma_f32 v[38:39], v[42:43], v[102:103], v[46:47]
	v_pk_fma_f32 v[66:67], v[50:51], v[102:103], v[66:67]
	v_pk_fma_f32 v[40:41], v[48:49], v[96:97], v[40:41]
	v_pk_mul_f32 v[32:33], v[32:33], v[44:45]
	v_pk_fma_f32 v[38:39], v[50:51], v[98:99], v[38:39]
	v_pk_mul_f32 v[34:35], v[34:35], v[36:37]
	v_pk_fma_f32 v[62:63], v[62:63], v[98:99], v[66:67]
	v_pk_mul_f32 v[58:59], v[58:59], v[60:61]
	v_pk_mul_f32 v[32:33], v[40:41], v[32:33]
	v_pk_mul_f32 v[34:35], v[38:39], v[34:35]
	v_pk_mul_f32 v[58:59], v[62:63], v[58:59]
	v_cvt_pk_bf16_f32 v32, v32, v33
	v_cvt_pk_bf16_f32 v33, v34, v35
	v_cvt_pk_bf16_f32 v57, v58, v59
	global_store_dwordx2 v[140:141], v[32:33], off offset:8
	v_mov_b32_e32 v65, 0
	v_mov_b32_e32 v66, 0
	v_mov_b32_e32 v67, 0
	v_mov_b32_e32 v40, 0
	v_mov_b32_e32 v41, 0
	v_mov_b32_e32 v42, 0
	v_mov_b32_e32 v43, 0
	v_mov_b32_e32 v32, 0
	v_mov_b32_e32 v33, 0
	v_mov_b32_e32 v34, 0
	v_mov_b32_e32 v35, 0
	v_mov_b32_e32 v36, 0
	v_mov_b32_e32 v37, 0
	v_mov_b32_e32 v38, 0
	v_mov_b32_e32 v39, 0
	global_store_dwordx2 v[152:153], v[56:57], off offset:8
	s_and_saveexec_b64 s[40:41], s[28:29]
	s_cbranch_execz .LBB0_754
	ds_read_b128 v[36:39], v237 offset:2064
	ds_read_b128 v[40:43], v237 offset:2576
	ds_read_b128 v[32:35], v237 offset:3088
	ds_read_b128 v[64:67], v237 offset:3600
	s_branch .LBB0_754

; #define LAS __attribute__((address_space(3)))
; __device__ __forceinline__ float sigmoidf_(float x) { return __builtin_amdgcn_rcpf(1.0f + __expf(-x)); }
;     __device__ __forceinline__ void operator()(AccRef acc, const Unit& u, int wr, int wc, int fr, int fq) const {
;     ...
;                 f32x4 h2v = (f32x4){0.f, 0.f, 0.f, 0.f}, h3v = h2v, h2g = h2v, h3g = h2v;
;                 const int pb = ai * 2 + wr - 1;
;                 if (pb >= 0 && fr == 0) { const LAS float* xp = xch + (pb * 2) * 256 + clb + 4 * n;
;                     h2v = *(const LAS f32x4*)(xp); h3v = *(const LAS f32x4*)(xp + 256); h2g = *(const LAS f32x4*)(xp + 128); h3g = *(const LAS f32x4*)(xp + 256 + 128); }
;                 float o[4][4];
; #pragma unroll
;                 for (int j = 0; j < 4; ++j) {
;                     const float v0 = acc[ai][0][0][n][j], v1 = acc[ai][0][1][n][j], v2 = acc[ai][0][2][n][j], v3 = acc[ai][0][3][n][j];
;                     const float g0 = acc[ai][1][0][n][j], g1 = acc[ai][1][1][n][j], g2 = acc[ai][1][2][n][j], g3 = acc[ai][1][3][n][j];
;                     const float pv3 = dpp_upd<0x111>(h3v[j], v3), pv2 = dpp_upd<0x111>(h2v[j], v2), pg3 = dpp_upd<0x111>(h3g[j], g3), pg2 = dpp_upd<0x111>(h2g[j], g2);
;                     const float hv0 = bvv[j] + w2v[j] * v0 + w1v[j] * pv3 + w0v[j] * pv2, hv1 = bvv[j] + w2v[j] * v1 + w1v[j] * v0 + w0v[j] * pv3;
;                     const float hv2 = bvv[j] + w2v[j] * v2 + w1v[j] * v1 + w0v[j] * v0, hv3 = bvv[j] + w2v[j] * v3 + w1v[j] * v2 + w0v[j] * v1;
;                     const float hg0 = bvg[j] + w2g[j] * g0 + w1g[j] * pg3 + w0g[j] * pg2, hg1 = bvg[j] + w2g[j] * g1 + w1g[j] * g0 + w0g[j] * pg3;
;                     const float hg2 = bvg[j] + w2g[j] * g2 + w1g[j] * g1 + w0g[j] * g0, hg3 = bvg[j] + w2g[j] * g3 + w1g[j] * g2 + w0g[j] * g1;
;                     o[0][j] = hg0 * sigmoidf_(hg0) * hv0; o[1][j] = hg1 * sigmoidf_(hg1) * hv1; o[2][j] = hg2 * sigmoidf_(hg2) * hv2; o[3][j] = hg3 * sigmoidf_(hg3) * hv3; }
; #pragma unroll
;                 for (int m = 0; m < 4; ++m) { u32x2 w; w.x = cvt_pk_bf16(o[m][0], o[m][1]); w.y = cvt_pk_bf16(o[m][2], o[m][3]);
;                     *(u32x2*)(Aout + (size_t)(row0 + ai * 128 + m) * FH + hc0 + 4 * n) = w; } } }
.LBB0_1368:
	s_or_b64 exec, exec, s[44:45]
	s_waitcnt lgkmcnt(0)
	v_mov_b32_dpp v198, v140 row_shr:1 row_mask:0xf bank_mask:0xf
	v_mov_b32_dpp v199, v141 row_shr:1 row_mask:0xf bank_mask:0xf
	s_waitcnt vmcnt(8)
	v_pk_fma_f32 v[248:249], v[152:153], v[184:185], v[188:189]
	v_mov_b32_dpp v206, v128 row_shr:1 row_mask:0xf bank_mask:0xf
	v_mov_b32_dpp v207, v129 row_shr:1 row_mask:0xf bank_mask:0xf
	v_pk_fma_f32 v[248:249], v[180:181], v[198:199], v[248:249]
	v_mov_b32_dpp v194, v148 row_shr:1 row_mask:0xf bank_mask:0xf
	v_pk_fma_f32 v[206:207], v[176:177], v[206:207], v[248:249]
	v_mov_b32_dpp v195, v149 row_shr:1 row_mask:0xf bank_mask:0xf
	v_mul_f32_e32 v193, 0xbfb8aa3b, v206
	v_exp_f32_e32 v193, v193
	v_mul_f32_e32 v247, 0xbfb8aa3b, v207
	v_exp_f32_e32 v247, v247
	v_pk_fma_f32 v[250:251], v[156:157], v[168:169], v[172:173]
	v_add_f32_e32 v193, 1.0, v193
	v_rcp_f32_e32 v248, v193
	v_add_f32_e32 v193, 1.0, v247
	v_rcp_f32_e32 v249, v193
	v_mov_b32_dpp v202, v136 row_shr:1 row_mask:0xf bank_mask:0xf
	v_mov_b32_dpp v203, v137 row_shr:1 row_mask:0xf bank_mask:0xf
	v_pk_fma_f32 v[250:251], v[164:165], v[194:195], v[250:251]
	v_pk_mul_f32 v[206:207], v[206:207], v[248:249]
	v_pk_fma_f32 v[202:203], v[160:161], v[202:203], v[250:251]
	v_mov_b32_dpp v200, v142 row_shr:1 row_mask:0xf bank_mask:0xf
	v_mov_b32_dpp v201, v143 row_shr:1 row_mask:0xf bank_mask:0xf
	v_pk_mul_f32 v[202:203], v[202:203], v[206:207]
	v_pk_fma_f32 v[206:207], v[154:155], v[186:187], v[190:191]
	v_mov_b32_dpp v208, v130 row_shr:1 row_mask:0xf bank_mask:0xf
	v_mov_b32_dpp v209, v131 row_shr:1 row_mask:0xf bank_mask:0xf
	v_pk_fma_f32 v[206:207], v[182:183], v[200:201], v[206:207]
	v_mov_b32_dpp v196, v150 row_shr:1 row_mask:0xf bank_mask:0xf
	v_pk_fma_f32 v[206:207], v[178:179], v[208:209], v[206:207]
	v_mov_b32_dpp v197, v151 row_shr:1 row_mask:0xf bank_mask:0xf
	v_mul_f32_e32 v193, 0xbfb8aa3b, v206
	v_exp_f32_e32 v193, v193
	v_mul_f32_e32 v208, 0xbfb8aa3b, v207
	v_exp_f32_e32 v209, v208
	v_cvt_pk_bf16_f32 v208, v202, v203
	v_add_f32_e32 v193, 1.0, v193
	v_rcp_f32_e32 v202, v193
	v_add_f32_e32 v193, 1.0, v209
	v_rcp_f32_e32 v203, v193
	v_pk_fma_f32 v[248:249], v[158:159], v[170:171], v[174:175]
	v_mov_b32_dpp v204, v138 row_shr:1 row_mask:0xf bank_mask:0xf
	v_mov_b32_dpp v205, v139 row_shr:1 row_mask:0xf bank_mask:0xf
	v_pk_fma_f32 v[248:249], v[166:167], v[196:197], v[248:249]
	v_pk_mul_f32 v[202:203], v[206:207], v[202:203]
	v_pk_fma_f32 v[204:205], v[162:163], v[204:205], v[248:249]
	v_lshl_add_u32 v246, s42, 8, v236
	v_pk_mul_f32 v[202:203], v[204:205], v[202:203]
	v_lshlrev_b64 v[204:205], 1, v[232:233]
	v_pk_fma_f32 v[232:233], v[132:133], v[184:185], v[188:189]
	v_mov_b64_e32 v[206:207], s[60:61]
	v_pk_fma_f32 v[232:233], v[152:153], v[180:181], v[232:233]
	v_cvt_pk_bf16_f32 v209, v202, v203
	v_pk_fma_f32 v[198:199], v[176:177], v[198:199], v[232:233]
	v_mad_i64_i32 v[202:203], s[42:43], v246, s82, v[206:207]
	v_mul_f32_e32 v193, 0xbfb8aa3b, v198
	v_exp_f32_e32 v193, v193
	v_mul_f32_e32 v232, 0xbfb8aa3b, v199
	v_exp_f32_e32 v232, v232
	v_lshl_add_u64 v[202:203], v[202:203], 0, v[204:205]
	v_add_f32_e32 v193, 1.0, v193
	global_store_dwordx2 v[202:203], v[208:209], off
	v_rcp_f32_e32 v208, v193
	v_add_f32_e32 v193, 1.0, v232
	v_rcp_f32_e32 v209, v193
	v_pk_fma_f32 v[232:233], v[144:145], v[168:169], v[172:173]
	v_pk_fma_f32 v[140:141], v[140:141], v[184:185], v[188:189]
	v_pk_fma_f32 v[232:233], v[156:157], v[164:165], v[232:233]
	v_pk_mul_f32 v[198:199], v[198:199], v[208:209]
	v_pk_fma_f32 v[194:195], v[160:161], v[194:195], v[232:233]
	v_pk_fma_f32 v[208:209], v[146:147], v[170:171], v[174:175]
	v_pk_mul_f32 v[194:195], v[194:195], v[198:199]
	v_pk_fma_f32 v[198:199], v[134:135], v[186:187], v[190:191]
	v_pk_fma_f32 v[208:209], v[158:159], v[166:167], v[208:209]
	v_pk_fma_f32 v[198:199], v[154:155], v[182:183], v[198:199]
	v_pk_fma_f32 v[196:197], v[162:163], v[196:197], v[208:209]
	v_pk_fma_f32 v[198:199], v[178:179], v[200:201], v[198:199]
	v_cvt_pk_bf16_f32 v194, v194, v195
	v_mul_f32_e32 v193, 0xbfb8aa3b, v198
	v_exp_f32_e32 v193, v193
	v_mul_f32_e32 v200, 0xbfb8aa3b, v199
	v_exp_f32_e32 v201, v200
	v_pk_fma_f32 v[148:149], v[148:149], v[168:169], v[172:173]
	v_add_f32_e32 v193, 1.0, v193
; #define LAS __attribute__((address_space(3)))
; __device__ __forceinline__ float sigmoidf_(float x) { return __builtin_amdgcn_rcpf(1.0f + __expf(-x)); }
;     __device__ __forceinline__ void operator()(AccRef acc, const Unit& u, int wr, int wc, int fr, int fq) const {
;     ...
;                 f32x4 h2v = (f32x4){0.f, 0.f, 0.f, 0.f}, h3v = h2v, h2g = h2v, h3g = h2v;
;                 const int pb = ai * 2 + wr - 1;
;                 if (pb >= 0 && fr == 0) { const LAS float* xp = xch + (pb * 2) * 256 + clb + 4 * n;
;                     h2v = *(const LAS f32x4*)(xp); h3v = *(const LAS f32x4*)(xp + 256); h2g = *(const LAS f32x4*)(xp + 128); h3g = *(const LAS f32x4*)(xp + 256 + 128); }
;     ...
;                     o[0][j] = hg0 * sigmoidf_(hg0) * hv0; o[1][j] = hg1 * sigmoidf_(hg1) * hv1; o[2][j] = hg2 * sigmoidf_(hg2) * hv2; o[3][j] = hg3 * sigmoidf_(hg3) * hv3; }
; #pragma unroll
;                 for (int m = 0; m < 4; ++m) { u32x2 w; w.x = cvt_pk_bf16(o[m][0], o[m][1]); w.y = cvt_pk_bf16(o[m][2], o[m][3]);
;                     *(u32x2*)(Aout + (size_t)(row0 + ai * 128 + m) * FH + hc0 + 4 * n) = w; } } }
	v_rcp_f32_e32 v200, v193
	v_add_f32_e32 v193, 1.0, v201
	v_rcp_f32_e32 v201, v193
	v_or_b32_e32 v193, 1, v246
	v_pk_mul_f32 v[198:199], v[198:199], v[200:201]
	s_nop 0
	v_pk_mul_f32 v[196:197], v[196:197], v[198:199]
	v_pk_fma_f32 v[198:199], v[128:129], v[184:185], v[188:189]
	v_cvt_pk_bf16_f32 v195, v196, v197
	v_pk_fma_f32 v[198:199], v[132:133], v[180:181], v[198:199]
	v_mad_i64_i32 v[196:197], s[42:43], v193, s82, v[206:207]
	v_pk_fma_f32 v[152:153], v[152:153], v[176:177], v[198:199]
	v_lshl_add_u64 v[196:197], v[196:197], 0, v[204:205]
	v_mul_f32_e32 v193, 0xbfb8aa3b, v152
	v_exp_f32_e32 v193, v193
	v_mul_f32_e32 v198, 0xbfb8aa3b, v153
	v_exp_f32_e32 v198, v198
	global_store_dwordx2 v[196:197], v[194:195], off
	v_add_f32_e32 v193, 1.0, v193
	v_rcp_f32_e32 v194, v193
	v_add_f32_e32 v193, 1.0, v198
	v_rcp_f32_e32 v195, v193
	v_pk_fma_f32 v[198:199], v[136:137], v[168:169], v[172:173]
	v_pk_fma_f32 v[128:129], v[128:129], v[180:181], v[140:141]
	v_pk_fma_f32 v[198:199], v[144:145], v[164:165], v[198:199]
	v_pk_fma_f32 v[128:129], v[132:133], v[176:177], v[128:129]
	v_pk_fma_f32 v[156:157], v[156:157], v[160:161], v[198:199]
	v_pk_mul_f32 v[152:153], v[152:153], v[194:195]
	v_mul_f32_e32 v132, 0xbfb8aa3b, v128
	v_pk_mul_f32 v[152:153], v[156:157], v[152:153]
	v_pk_fma_f32 v[156:157], v[130:131], v[186:187], v[190:191]
	v_exp_f32_e32 v140, v132
	v_pk_fma_f32 v[132:133], v[142:143], v[186:187], v[190:191]
	v_pk_fma_f32 v[156:157], v[134:135], v[182:183], v[156:157]
	v_pk_fma_f32 v[130:131], v[130:131], v[182:183], v[132:133]
	v_pk_fma_f32 v[154:155], v[154:155], v[178:179], v[156:157]
	v_pk_fma_f32 v[130:131], v[134:135], v[178:179], v[130:131]
	v_mul_f32_e32 v156, 0xbfb8aa3b, v154
	v_mul_f32_e32 v141, 0xbfb8aa3b, v129
	v_mul_f32_e32 v132, 0xbfb8aa3b, v130
	v_mul_f32_e32 v133, 0xbfb8aa3b, v131
	v_exp_f32_e32 v157, v156
	v_mul_f32_e32 v156, 0xbfb8aa3b, v155
	v_exp_f32_e32 v141, v141
	v_exp_f32_e32 v132, v132
	v_exp_f32_e32 v133, v133
	v_exp_f32_e32 v193, v156
	v_add_f32_e32 v140, 1.0, v140
	v_add_f32_e32 v141, 1.0, v141
	v_add_f32_e32 v132, 1.0, v132
	v_add_f32_e32 v133, 1.0, v133
	v_cvt_pk_bf16_f32 v156, v152, v153
	v_add_f32_e32 v152, 1.0, v157
	v_add_f32_e32 v153, 1.0, v193
	v_rcp_f32_e32 v140, v140
	v_rcp_f32_e32 v141, v141
	v_rcp_f32_e32 v132, v132
	v_rcp_f32_e32 v133, v133
	v_rcp_f32_e32 v152, v152
	v_rcp_f32_e32 v153, v153
	v_pk_fma_f32 v[142:143], v[150:151], v[170:171], v[174:175]
	v_pk_fma_f32 v[194:195], v[138:139], v[170:171], v[174:175]
	v_pk_fma_f32 v[136:137], v[136:137], v[164:165], v[148:149]
	v_pk_fma_f32 v[134:135], v[138:139], v[166:167], v[142:143]
	v_pk_fma_f32 v[194:195], v[146:147], v[166:167], v[194:195]
	v_pk_fma_f32 v[136:137], v[144:145], v[160:161], v[136:137]
	v_pk_mul_f32 v[128:129], v[128:129], v[140:141]
	v_pk_fma_f32 v[134:135], v[146:147], v[162:163], v[134:135]
	v_pk_mul_f32 v[130:131], v[130:131], v[132:133]
	v_pk_fma_f32 v[158:159], v[158:159], v[162:163], v[194:195]
	v_pk_mul_f32 v[152:153], v[154:155], v[152:153]
	v_pk_mul_f32 v[128:129], v[136:137], v[128:129]
	v_pk_mul_f32 v[130:131], v[134:135], v[130:131]
	v_pk_mul_f32 v[152:153], v[158:159], v[152:153]
	v_cvt_pk_bf16_f32 v128, v128, v129
	v_cvt_pk_bf16_f32 v129, v130, v131
	v_or_b32_e32 v130, 3, v246
	v_cvt_pk_bf16_f32 v157, v152, v153
	v_or_b32_e32 v152, 2, v246
	v_mad_i64_i32 v[130:131], s[42:43], v130, s82, v[206:207]
	v_mad_i64_i32 v[152:153], s[42:43], v152, s82, v[206:207]
	v_lshl_add_u64 v[140:141], v[130:131], 0, v[204:205]
	v_lshl_add_u64 v[152:153], v[152:153], 0, v[204:205]
	global_store_dwordx2 v[140:141], v[128:129], off
	v_mov_b32_e32 v193, 0
	v_mov_b32_e32 v194, 0
	v_mov_b32_e32 v195, 0
	v_mov_b32_e32 v136, 0
	v_mov_b32_e32 v137, 0
	v_mov_b32_e32 v138, 0
	v_mov_b32_e32 v139, 0
	v_mov_b32_e32 v128, 0
	v_mov_b32_e32 v129, 0
	v_mov_b32_e32 v130, 0
	v_mov_b32_e32 v131, 0
	v_mov_b32_e32 v132, 0
	v_mov_b32_e32 v133, 0
	v_mov_b32_e32 v134, 0
	v_mov_b32_e32 v135, 0
	global_store_dwordx2 v[152:153], v[156:157], off
	s_and_saveexec_b64 s[42:43], s[30:31]
	s_cbranch_execz .LBB0_1370
	ds_read_b128 v[132:135], v237 offset:2048
	ds_read_b128 v[136:139], v237 offset:2560
	ds_read_b128 v[128:131], v237 offset:3072
	ds_read_b128 v[192:195], v237 offset:3584

; __device__ __forceinline__ float sigmoidf_(float x) { return __builtin_amdgcn_rcpf(1.0f + __expf(-x)); }
;     __device__ __forceinline__ void operator()(AccRef acc, const Unit& u, int wr, int wc, int fr, int fq) const {
;     ...
;                 float o[4][4];
; #pragma unroll
;                 for (int j = 0; j < 4; ++j) {
;                     const float v0 = acc[ai][0][0][n][j], v1 = acc[ai][0][1][n][j], v2 = acc[ai][0][2][n][j], v3 = acc[ai][0][3][n][j];
;                     const float g0 = acc[ai][1][0][n][j], g1 = acc[ai][1][1][n][j], g2 = acc[ai][1][2][n][j], g3 = acc[ai][1][3][n][j];
;                     const float pv3 = dpp_upd<0x111>(h3v[j], v3), pv2 = dpp_upd<0x111>(h2v[j], v2), pg3 = dpp_upd<0x111>(h3g[j], g3), pg2 = dpp_upd<0x111>(h2g[j], g2);
;                     const float hv0 = bvv[j] + w2v[j] * v0 + w1v[j] * pv3 + w0v[j] * pv2, hv1 = bvv[j] + w2v[j] * v1 + w1v[j] * v0 + w0v[j] * pv3;
;                     const float hv2 = bvv[j] + w2v[j] * v2 + w1v[j] * v1 + w0v[j] * v0, hv3 = bvv[j] + w2v[j] * v3 + w1v[j] * v2 + w0v[j] * v1;
;                     const float hg0 = bvg[j] + w2g[j] * g0 + w1g[j] * pg3 + w0g[j] * pg2, hg1 = bvg[j] + w2g[j] * g1 + w1g[j] * g0 + w0g[j] * pg3;
;                     const float hg2 = bvg[j] + w2g[j] * g2 + w1g[j] * g1 + w0g[j] * g0, hg3 = bvg[j] + w2g[j] * g3 + w1g[j] * g2 + w0g[j] * g1;
;                     o[0][j] = hg0 * sigmoidf_(hg0) * hv0; o[1][j] = hg1 * sigmoidf_(hg1) * hv1; o[2][j] = hg2 * sigmoidf_(hg2) * hv2; o[3][j] = hg3 * sigmoidf_(hg3) * hv3; }
; #pragma unroll
;                 for (int m = 0; m < 4; ++m) { u32x2 w; w.x = cvt_pk_bf16(o[m][0], o[m][1]); w.y = cvt_pk_bf16(o[m][2], o[m][3]);
;                     *(u32x2*)(Aout + (size_t)(row0 + ai * 128 + m) * FH + hc0 + 4 * n) = w; } } }
.LBB0_1372:
	s_or_b64 exec, exec, s[42:43]
	s_waitcnt lgkmcnt(0)
	v_mov_b32_dpp v70, v44 row_shr:1 row_mask:0xf bank_mask:0xf
	v_mov_b32_dpp v71, v45 row_shr:1 row_mask:0xf bank_mask:0xf
	s_waitcnt vmcnt(8)
	v_pk_fma_f32 v[84:85], v[56:57], v[120:121], v[124:125]
	v_mov_b32_dpp v78, v32 row_shr:1 row_mask:0xf bank_mask:0xf
	v_mov_b32_dpp v79, v33 row_shr:1 row_mask:0xf bank_mask:0xf
	v_pk_fma_f32 v[84:85], v[116:117], v[70:71], v[84:85]
	v_mov_b32_dpp v66, v52 row_shr:1 row_mask:0xf bank_mask:0xf
	v_pk_fma_f32 v[78:79], v[112:113], v[78:79], v[84:85]
	v_mov_b32_dpp v67, v53 row_shr:1 row_mask:0xf bank_mask:0xf
	v_mul_f32_e32 v65, 0xbfb8aa3b, v78
	v_exp_f32_e32 v65, v65
	v_mul_f32_e32 v84, 0xbfb8aa3b, v79
	v_exp_f32_e32 v85, v84
	v_pk_fma_f32 v[86:87], v[60:61], v[104:105], v[108:109]
	v_add_f32_e32 v65, 1.0, v65
	v_rcp_f32_e32 v84, v65
	v_add_f32_e32 v65, 1.0, v85
	v_rcp_f32_e32 v85, v65
	v_mov_b32_dpp v74, v40 row_shr:1 row_mask:0xf bank_mask:0xf
	v_mov_b32_dpp v75, v41 row_shr:1 row_mask:0xf bank_mask:0xf
	v_pk_fma_f32 v[86:87], v[100:101], v[66:67], v[86:87]
	v_pk_mul_f32 v[78:79], v[78:79], v[84:85]
	v_pk_fma_f32 v[74:75], v[96:97], v[74:75], v[86:87]
	v_mov_b32_dpp v72, v46 row_shr:1 row_mask:0xf bank_mask:0xf
	v_mov_b32_dpp v73, v47 row_shr:1 row_mask:0xf bank_mask:0xf
	v_pk_mul_f32 v[74:75], v[74:75], v[78:79]
	v_pk_fma_f32 v[78:79], v[58:59], v[122:123], v[126:127]
	v_mov_b32_dpp v80, v34 row_shr:1 row_mask:0xf bank_mask:0xf
	v_mov_b32_dpp v81, v35 row_shr:1 row_mask:0xf bank_mask:0xf
	v_pk_fma_f32 v[78:79], v[118:119], v[72:73], v[78:79]
	v_mov_b32_dpp v68, v54 row_shr:1 row_mask:0xf bank_mask:0xf
	v_pk_fma_f32 v[78:79], v[114:115], v[80:81], v[78:79]
	v_mov_b32_dpp v69, v55 row_shr:1 row_mask:0xf bank_mask:0xf
	v_mul_f32_e32 v65, 0xbfb8aa3b, v78
	v_exp_f32_e32 v65, v65
	v_mul_f32_e32 v80, 0xbfb8aa3b, v79
	v_exp_f32_e32 v81, v80
	v_pk_fma_f32 v[84:85], v[62:63], v[106:107], v[110:111]
	v_add_f32_e32 v65, 1.0, v65
	v_rcp_f32_e32 v80, v65
	v_add_f32_e32 v65, 1.0, v81
	v_rcp_f32_e32 v81, v65
	v_mov_b32_dpp v76, v42 row_shr:1 row_mask:0xf bank_mask:0xf
	v_mov_b32_dpp v77, v43 row_shr:1 row_mask:0xf bank_mask:0xf
	v_pk_fma_f32 v[84:85], v[102:103], v[68:69], v[84:85]
	v_pk_mul_f32 v[78:79], v[78:79], v[80:81]
	v_pk_fma_f32 v[76:77], v[98:99], v[76:77], v[84:85]
	v_cvt_pk_bf16_f32 v74, v74, v75
	v_pk_mul_f32 v[76:77], v[76:77], v[78:79]
	v_pk_fma_f32 v[44:45], v[44:45], v[120:121], v[124:125]
	v_cvt_pk_bf16_f32 v75, v76, v77
	v_pk_fma_f32 v[76:77], v[36:37], v[120:121], v[124:125]
	global_store_dwordx2 v[202:203], v[74:75], off offset:8
	v_pk_fma_f32 v[76:77], v[56:57], v[116:117], v[76:77]
	v_pk_fma_f32 v[52:53], v[52:53], v[104:105], v[108:109]
	v_pk_fma_f32 v[70:71], v[112:113], v[70:71], v[76:77]
	s_nop 0
	v_mul_f32_e32 v65, 0xbfb8aa3b, v70
	v_exp_f32_e32 v65, v65
	v_mul_f32_e32 v76, 0xbfb8aa3b, v71
	v_exp_f32_e32 v76, v76
	v_add_f32_e32 v65, 1.0, v65
	v_rcp_f32_e32 v74, v65
	v_add_f32_e32 v65, 1.0, v76
	v_rcp_f32_e32 v75, v65
	v_pk_fma_f32 v[76:77], v[48:49], v[104:105], v[108:109]
	v_pk_mul_f32 v[70:71], v[70:71], v[74:75]
	v_pk_fma_f32 v[76:77], v[60:61], v[100:101], v[76:77]
	v_pk_fma_f32 v[74:75], v[50:51], v[106:107], v[110:111]
	v_pk_fma_f32 v[66:67], v[96:97], v[66:67], v[76:77]
	v_pk_fma_f32 v[74:75], v[62:63], v[102:103], v[74:75]
	v_pk_mul_f32 v[66:67], v[66:67], v[70:71]
	v_pk_fma_f32 v[70:71], v[38:39], v[122:123], v[126:127]
	v_pk_fma_f32 v[68:69], v[98:99], v[68:69], v[74:75]
	v_pk_fma_f32 v[70:71], v[58:59], v[118:119], v[70:71]
	v_cvt_pk_bf16_f32 v66, v66, v67
	v_pk_fma_f32 v[70:71], v[114:115], v[72:73], v[70:71]
	s_nop 0
	v_mul_f32_e32 v65, 0xbfb8aa3b, v70
	v_exp_f32_e32 v65, v65
; #define LAS __attribute__((address_space(3)))
; __device__ __forceinline__ float sigmoidf_(float x) { return __builtin_amdgcn_rcpf(1.0f + __expf(-x)); }
;     __device__ __forceinline__ void operator()(AccRef acc, const Unit& u, int wr, int wc, int fr, int fq) const {
;     ...
;                 f32x4 h2v = (f32x4){0.f, 0.f, 0.f, 0.f}, h3v = h2v, h2g = h2v, h3g = h2v;
;                 const int pb = ai * 2 + wr - 1;
;                 if (pb >= 0 && fr == 0) { const LAS float* xp = xch + (pb * 2) * 256 + clb + 4 * n;
;                     h2v = *(const LAS f32x4*)(xp); h3v = *(const LAS f32x4*)(xp + 256); h2g = *(const LAS f32x4*)(xp + 128); h3g = *(const LAS f32x4*)(xp + 256 + 128); }
;                 float o[4][4];
; #pragma unroll
;                 for (int j = 0; j < 4; ++j) {
;                     const float v0 = acc[ai][0][0][n][j], v1 = acc[ai][0][1][n][j], v2 = acc[ai][0][2][n][j], v3 = acc[ai][0][3][n][j];
;                     const float g0 = acc[ai][1][0][n][j], g1 = acc[ai][1][1][n][j], g2 = acc[ai][1][2][n][j], g3 = acc[ai][1][3][n][j];
;                     const float pv3 = dpp_upd<0x111>(h3v[j], v3), pv2 = dpp_upd<0x111>(h2v[j], v2), pg3 = dpp_upd<0x111>(h3g[j], g3), pg2 = dpp_upd<0x111>(h2g[j], g2);
;                     const float hv0 = bvv[j] + w2v[j] * v0 + w1v[j] * pv3 + w0v[j] * pv2, hv1 = bvv[j] + w2v[j] * v1 + w1v[j] * v0 + w0v[j] * pv3;
;                     const float hv2 = bvv[j] + w2v[j] * v2 + w1v[j] * v1 + w0v[j] * v0, hv3 = bvv[j] + w2v[j] * v3 + w1v[j] * v2 + w0v[j] * v1;
;                     const float hg0 = bvg[j] + w2g[j] * g0 + w1g[j] * pg3 + w0g[j] * pg2, hg1 = bvg[j] + w2g[j] * g1 + w1g[j] * g0 + w0g[j] * pg3;
;                     const float hg2 = bvg[j] + w2g[j] * g2 + w1g[j] * g1 + w0g[j] * g0, hg3 = bvg[j] + w2g[j] * g3 + w1g[j] * g2 + w0g[j] * g1;
;                     o[0][j] = hg0 * sigmoidf_(hg0) * hv0; o[1][j] = hg1 * sigmoidf_(hg1) * hv1; o[2][j] = hg2 * sigmoidf_(hg2) * hv2; o[3][j] = hg3 * sigmoidf_(hg3) * hv3; }
; #pragma unroll
;                 for (int m = 0; m < 4; ++m) { u32x2 w; w.x = cvt_pk_bf16(o[m][0], o[m][1]); w.y = cvt_pk_bf16(o[m][2], o[m][3]);
;                     *(u32x2*)(Aout + (size_t)(row0 + ai * 128 + m) * FH + hc0 + 4 * n) = w; } } }
	v_mul_f32_e32 v72, 0xbfb8aa3b, v71
	v_exp_f32_e32 v73, v72
	v_add_f32_e32 v65, 1.0, v65
	v_rcp_f32_e32 v72, v65
	v_add_f32_e32 v65, 1.0, v73
	v_rcp_f32_e32 v73, v65
	s_nop 0
	v_pk_mul_f32 v[70:71], v[70:71], v[72:73]
	s_nop 0
	v_pk_mul_f32 v[68:69], v[68:69], v[70:71]
	s_nop 0
	v_cvt_pk_bf16_f32 v67, v68, v69
	v_pk_fma_f32 v[68:69], v[32:33], v[120:121], v[124:125]
	global_store_dwordx2 v[196:197], v[66:67], off offset:8
	v_pk_fma_f32 v[68:69], v[36:37], v[116:117], v[68:69]
	v_pk_fma_f32 v[32:33], v[32:33], v[116:117], v[44:45]
	v_pk_fma_f32 v[56:57], v[56:57], v[112:113], v[68:69]
	v_pk_fma_f32 v[32:33], v[36:37], v[112:113], v[32:33]
	v_mul_f32_e32 v65, 0xbfb8aa3b, v56
	v_exp_f32_e32 v65, v65
	v_mul_f32_e32 v68, 0xbfb8aa3b, v57
	v_exp_f32_e32 v68, v68
	v_mul_f32_e32 v36, 0xbfb8aa3b, v32
	v_add_f32_e32 v65, 1.0, v65
	v_rcp_f32_e32 v66, v65
	v_add_f32_e32 v65, 1.0, v68
	v_rcp_f32_e32 v67, v65
	v_pk_fma_f32 v[68:69], v[40:41], v[104:105], v[108:109]
	v_exp_f32_e32 v44, v36
	v_pk_fma_f32 v[68:69], v[48:49], v[100:101], v[68:69]
	v_pk_mul_f32 v[56:57], v[56:57], v[66:67]
	v_pk_fma_f32 v[60:61], v[60:61], v[96:97], v[68:69]
	v_pk_fma_f32 v[36:37], v[46:47], v[122:123], v[126:127]
	v_pk_mul_f32 v[56:57], v[60:61], v[56:57]
	v_pk_fma_f32 v[60:61], v[34:35], v[122:123], v[126:127]
	v_pk_fma_f32 v[34:35], v[34:35], v[118:119], v[36:37]
	v_pk_fma_f32 v[60:61], v[38:39], v[118:119], v[60:61]
	v_pk_fma_f32 v[34:35], v[38:39], v[114:115], v[34:35]
	v_pk_fma_f32 v[58:59], v[58:59], v[114:115], v[60:61]
	v_mul_f32_e32 v45, 0xbfb8aa3b, v33
	v_mul_f32_e32 v60, 0xbfb8aa3b, v58
	v_mul_f32_e32 v36, 0xbfb8aa3b, v34
	v_mul_f32_e32 v37, 0xbfb8aa3b, v35
	v_exp_f32_e32 v60, v60
	v_mul_f32_e32 v61, 0xbfb8aa3b, v59
	v_exp_f32_e32 v45, v45
	v_exp_f32_e32 v36, v36
	v_exp_f32_e32 v37, v37
	v_exp_f32_e32 v61, v61
	v_cvt_pk_bf16_f32 v56, v56, v57
	v_add_f32_e32 v57, 1.0, v60
	v_add_f32_e32 v44, 1.0, v44
	v_add_f32_e32 v45, 1.0, v45
	v_add_f32_e32 v36, 1.0, v36
	v_add_f32_e32 v37, 1.0, v37
	v_rcp_f32_e32 v60, v57
	v_add_f32_e32 v57, 1.0, v61
	v_rcp_f32_e32 v44, v44
	v_rcp_f32_e32 v45, v45
	v_rcp_f32_e32 v36, v36
	v_rcp_f32_e32 v37, v37
	v_rcp_f32_e32 v61, v57
	v_pk_fma_f32 v[46:47], v[54:55], v[106:107], v[110:111]
	v_pk_fma_f32 v[66:67], v[42:43], v[106:107], v[110:111]
	v_pk_fma_f32 v[40:41], v[40:41], v[100:101], v[52:53]
	v_pk_fma_f32 v[38:39], v[42:43], v[102:103], v[46:47]
	v_pk_fma_f32 v[66:67], v[50:51], v[102:103], v[66:67]
	v_pk_fma_f32 v[40:41], v[48:49], v[96:97], v[40:41]
	v_pk_mul_f32 v[32:33], v[32:33], v[44:45]
	v_pk_fma_f32 v[38:39], v[50:51], v[98:99], v[38:39]
	v_pk_mul_f32 v[34:35], v[34:35], v[36:37]
	v_pk_fma_f32 v[62:63], v[62:63], v[98:99], v[66:67]
	v_pk_mul_f32 v[58:59], v[58:59], v[60:61]
	v_pk_mul_f32 v[32:33], v[40:41], v[32:33]
	v_pk_mul_f32 v[34:35], v[38:39], v[34:35]
	v_pk_mul_f32 v[58:59], v[62:63], v[58:59]
	v_cvt_pk_bf16_f32 v32, v32, v33
	v_cvt_pk_bf16_f32 v33, v34, v35
	v_cvt_pk_bf16_f32 v57, v58, v59
	global_store_dwordx2 v[140:141], v[32:33], off offset:8
	v_mov_b32_e32 v65, 0
	v_mov_b32_e32 v66, 0
	v_mov_b32_e32 v67, 0
	v_mov_b32_e32 v40, 0
	v_mov_b32_e32 v41, 0
	v_mov_b32_e32 v42, 0
	v_mov_b32_e32 v43, 0
	v_mov_b32_e32 v32, 0
	v_mov_b32_e32 v33, 0
	v_mov_b32_e32 v34, 0
	v_mov_b32_e32 v35, 0
	v_mov_b32_e32 v36, 0
	v_mov_b32_e32 v37, 0
	v_mov_b32_e32 v38, 0
	v_mov_b32_e32 v39, 0
	global_store_dwordx2 v[152:153], v[56:57], off offset:8
	s_and_saveexec_b64 s[42:43], s[30:31]
	s_cbranch_execz .LBB0_1355
	ds_read_b128 v[36:39], v237 offset:2064
	ds_read_b128 v[40:43], v237 offset:2576
	ds_read_b128 v[32:35], v237 offset:3088
	ds_read_b128 v[64:67], v237 offset:3600
	s_branch .LBB0_1355

; __device__ __forceinline__ float sigmoidf_(float x) { return __builtin_amdgcn_rcpf(1.0f + __expf(-x)); }
;     __device__ __forceinline__ void operator()(AccRef acc, const Unit& u, int wr, int wc, int fr, int fq) const {
;     ...
;                 float o[4][4];
; #pragma unroll
;                 for (int j = 0; j < 4; ++j) {
;                     const float v0 = acc[ai][0][0][n][j], v1 = acc[ai][0][1][n][j], v2 = acc[ai][0][2][n][j], v3 = acc[ai][0][3][n][j];
;                     const float g0 = acc[ai][1][0][n][j], g1 = acc[ai][1][1][n][j], g2 = acc[ai][1][2][n][j], g3 = acc[ai][1][3][n][j];
;                     const float pv3 = dpp_upd<0x111>(h3v[j], v3), pv2 = dpp_upd<0x111>(h2v[j], v2), pg3 = dpp_upd<0x111>(h3g[j], g3), pg2 = dpp_upd<0x111>(h2g[j], g2);
;                     const float hv0 = bvv[j] + w2v[j] * v0 + w1v[j] * pv3 + w0v[j] * pv2, hv1 = bvv[j] + w2v[j] * v1 + w1v[j] * v0 + w0v[j] * pv3;
;                     const float hv2 = bvv[j] + w2v[j] * v2 + w1v[j] * v1 + w0v[j] * v0, hv3 = bvv[j] + w2v[j] * v3 + w1v[j] * v2 + w0v[j] * v1;
;                     const float hg0 = bvg[j] + w2g[j] * g0 + w1g[j] * pg3 + w0g[j] * pg2, hg1 = bvg[j] + w2g[j] * g1 + w1g[j] * g0 + w0g[j] * pg3;
;                     const float hg2 = bvg[j] + w2g[j] * g2 + w1g[j] * g1 + w0g[j] * g0, hg3 = bvg[j] + w2g[j] * g3 + w1g[j] * g2 + w0g[j] * g1;
;                     o[0][j] = hg0 * sigmoidf_(hg0) * hv0; o[1][j] = hg1 * sigmoidf_(hg1) * hv1; o[2][j] = hg2 * sigmoidf_(hg2) * hv2; o[3][j] = hg3 * sigmoidf_(hg3) * hv3; }
; #pragma unroll
;                 for (int m = 0; m < 4; ++m) { u32x2 w; w.x = cvt_pk_bf16(o[m][0], o[m][1]); w.y = cvt_pk_bf16(o[m][2], o[m][3]);
;                     *(u32x2*)(Aout + (size_t)(row0 + ai * 128 + m) * FH + hc0 + 4 * n) = w; } } }
.LBB0_1949:
	s_or_b64 exec, exec, s[36:37]
	s_waitcnt lgkmcnt(0)
	v_mov_b32_dpp v198, v140 row_shr:1 row_mask:0xf bank_mask:0xf
	v_mov_b32_dpp v199, v141 row_shr:1 row_mask:0xf bank_mask:0xf
	s_waitcnt vmcnt(8)
	v_pk_fma_f32 v[246:247], v[152:153], v[184:185], v[188:189]
	v_mov_b32_dpp v206, v128 row_shr:1 row_mask:0xf bank_mask:0xf
	v_mov_b32_dpp v207, v129 row_shr:1 row_mask:0xf bank_mask:0xf
	v_pk_fma_f32 v[246:247], v[180:181], v[198:199], v[246:247]
	v_mov_b32_dpp v194, v148 row_shr:1 row_mask:0xf bank_mask:0xf
	v_pk_fma_f32 v[206:207], v[176:177], v[206:207], v[246:247]
	v_mov_b32_dpp v195, v149 row_shr:1 row_mask:0xf bank_mask:0xf
	v_mul_f32_e32 v193, 0xbfb8aa3b, v206
	v_exp_f32_e32 v193, v193
	v_mul_f32_e32 v246, 0xbfb8aa3b, v207
	v_exp_f32_e32 v247, v246
	v_pk_fma_f32 v[248:249], v[156:157], v[168:169], v[172:173]
	v_add_f32_e32 v193, 1.0, v193
	v_rcp_f32_e32 v246, v193
	v_add_f32_e32 v193, 1.0, v247
	v_rcp_f32_e32 v247, v193
	v_mov_b32_dpp v202, v136 row_shr:1 row_mask:0xf bank_mask:0xf
	v_mov_b32_dpp v203, v137 row_shr:1 row_mask:0xf bank_mask:0xf
	v_pk_fma_f32 v[248:249], v[164:165], v[194:195], v[248:249]
	v_pk_mul_f32 v[206:207], v[206:207], v[246:247]
	v_pk_fma_f32 v[202:203], v[160:161], v[202:203], v[248:249]
	v_mov_b32_dpp v200, v142 row_shr:1 row_mask:0xf bank_mask:0xf
	v_mov_b32_dpp v201, v143 row_shr:1 row_mask:0xf bank_mask:0xf
	v_pk_mul_f32 v[202:203], v[202:203], v[206:207]
	v_pk_fma_f32 v[206:207], v[154:155], v[186:187], v[190:191]
	v_mov_b32_dpp v208, v130 row_shr:1 row_mask:0xf bank_mask:0xf
	v_mov_b32_dpp v209, v131 row_shr:1 row_mask:0xf bank_mask:0xf
	v_pk_fma_f32 v[206:207], v[182:183], v[200:201], v[206:207]
	v_mov_b32_dpp v196, v150 row_shr:1 row_mask:0xf bank_mask:0xf
	v_pk_fma_f32 v[206:207], v[178:179], v[208:209], v[206:207]
	v_mov_b32_dpp v197, v151 row_shr:1 row_mask:0xf bank_mask:0xf
	v_mul_f32_e32 v193, 0xbfb8aa3b, v206
	v_exp_f32_e32 v193, v193
	v_mul_f32_e32 v208, 0xbfb8aa3b, v207
	v_exp_f32_e32 v209, v208
	v_cvt_pk_bf16_f32 v208, v202, v203
	v_add_f32_e32 v193, 1.0, v193
	v_rcp_f32_e32 v202, v193
	v_add_f32_e32 v193, 1.0, v209
	v_rcp_f32_e32 v203, v193
	v_pk_fma_f32 v[246:247], v[158:159], v[170:171], v[174:175]
	v_mov_b32_dpp v204, v138 row_shr:1 row_mask:0xf bank_mask:0xf
	v_mov_b32_dpp v205, v139 row_shr:1 row_mask:0xf bank_mask:0xf
	v_pk_fma_f32 v[246:247], v[166:167], v[196:197], v[246:247]
	v_pk_mul_f32 v[202:203], v[206:207], v[202:203]
	v_pk_fma_f32 v[204:205], v[162:163], v[204:205], v[246:247]
	v_lshl_add_u32 v245, s34, 8, v235
	v_pk_mul_f32 v[202:203], v[204:205], v[202:203]
	v_lshlrev_b64 v[204:205], 1, v[232:233]
	v_pk_fma_f32 v[232:233], v[132:133], v[184:185], v[188:189]
	v_mov_b64_e32 v[206:207], s[60:61]
	v_pk_fma_f32 v[232:233], v[152:153], v[180:181], v[232:233]
	v_cvt_pk_bf16_f32 v209, v202, v203
	v_pk_fma_f32 v[198:199], v[176:177], v[198:199], v[232:233]
	v_mad_i64_i32 v[202:203], s[34:35], v245, s63, v[206:207]
	v_mul_f32_e32 v193, 0xbfb8aa3b, v198
	v_exp_f32_e32 v193, v193
	v_mul_f32_e32 v232, 0xbfb8aa3b, v199
	v_exp_f32_e32 v232, v232
	v_lshl_add_u64 v[202:203], v[202:203], 0, v[204:205]
	v_add_f32_e32 v193, 1.0, v193
	global_store_dwordx2 v[202:203], v[208:209], off
	v_rcp_f32_e32 v208, v193
	v_add_f32_e32 v193, 1.0, v232
	v_rcp_f32_e32 v209, v193
	v_pk_fma_f32 v[232:233], v[144:145], v[168:169], v[172:173]
	v_pk_fma_f32 v[140:141], v[140:141], v[184:185], v[188:189]
	v_pk_fma_f32 v[232:233], v[156:157], v[164:165], v[232:233]
	v_pk_mul_f32 v[198:199], v[198:199], v[208:209]
	v_pk_fma_f32 v[194:195], v[160:161], v[194:195], v[232:233]
	v_pk_fma_f32 v[208:209], v[146:147], v[170:171], v[174:175]
	v_pk_mul_f32 v[194:195], v[194:195], v[198:199]
	v_pk_fma_f32 v[198:199], v[134:135], v[186:187], v[190:191]
	v_pk_fma_f32 v[208:209], v[158:159], v[166:167], v[208:209]
	v_pk_fma_f32 v[198:199], v[154:155], v[182:183], v[198:199]
	v_pk_fma_f32 v[196:197], v[162:163], v[196:197], v[208:209]
	v_pk_fma_f32 v[198:199], v[178:179], v[200:201], v[198:199]
	v_cvt_pk_bf16_f32 v194, v194, v195
	v_mul_f32_e32 v193, 0xbfb8aa3b, v198
	v_exp_f32_e32 v193, v193
	v_mul_f32_e32 v200, 0xbfb8aa3b, v199
	v_exp_f32_e32 v201, v200
	v_pk_fma_f32 v[148:149], v[148:149], v[168:169], v[172:173]
	v_add_f32_e32 v193, 1.0, v193
; #define LAS __attribute__((address_space(3)))
; __device__ __forceinline__ float sigmoidf_(float x) { return __builtin_amdgcn_rcpf(1.0f + __expf(-x)); }
;     __device__ __forceinline__ void operator()(AccRef acc, const Unit& u, int wr, int wc, int fr, int fq) const {
;     ...
;                 f32x4 h2v = (f32x4){0.f, 0.f, 0.f, 0.f}, h3v = h2v, h2g = h2v, h3g = h2v;
;                 const int pb = ai * 2 + wr - 1;
;                 if (pb >= 0 && fr == 0) { const LAS float* xp = xch + (pb * 2) * 256 + clb + 4 * n;
;                     h2v = *(const LAS f32x4*)(xp); h3v = *(const LAS f32x4*)(xp + 256); h2g = *(const LAS f32x4*)(xp + 128); h3g = *(const LAS f32x4*)(xp + 256 + 128); }
;                 float o[4][4];
; #pragma unroll
;                 for (int j = 0; j < 4; ++j) {
;                     const float v0 = acc[ai][0][0][n][j], v1 = acc[ai][0][1][n][j], v2 = acc[ai][0][2][n][j], v3 = acc[ai][0][3][n][j];
;                     const float g0 = acc[ai][1][0][n][j], g1 = acc[ai][1][1][n][j], g2 = acc[ai][1][2][n][j], g3 = acc[ai][1][3][n][j];
;                     const float pv3 = dpp_upd<0x111>(h3v[j], v3), pv2 = dpp_upd<0x111>(h2v[j], v2), pg3 = dpp_upd<0x111>(h3g[j], g3), pg2 = dpp_upd<0x111>(h2g[j], g2);
;                     const float hv0 = bvv[j] + w2v[j] * v0 + w1v[j] * pv3 + w0v[j] * pv2, hv1 = bvv[j] + w2v[j] * v1 + w1v[j] * v0 + w0v[j] * pv3;
;                     const float hv2 = bvv[j] + w2v[j] * v2 + w1v[j] * v1 + w0v[j] * v0, hv3 = bvv[j] + w2v[j] * v3 + w1v[j] * v2 + w0v[j] * v1;
;                     const float hg0 = bvg[j] + w2g[j] * g0 + w1g[j] * pg3 + w0g[j] * pg2, hg1 = bvg[j] + w2g[j] * g1 + w1g[j] * g0 + w0g[j] * pg3;
;                     const float hg2 = bvg[j] + w2g[j] * g2 + w1g[j] * g1 + w0g[j] * g0, hg3 = bvg[j] + w2g[j] * g3 + w1g[j] * g2 + w0g[j] * g1;
;                     o[0][j] = hg0 * sigmoidf_(hg0) * hv0; o[1][j] = hg1 * sigmoidf_(hg1) * hv1; o[2][j] = hg2 * sigmoidf_(hg2) * hv2; o[3][j] = hg3 * sigmoidf_(hg3) * hv3; }
; #pragma unroll
;                 for (int m = 0; m < 4; ++m) { u32x2 w; w.x = cvt_pk_bf16(o[m][0], o[m][1]); w.y = cvt_pk_bf16(o[m][2], o[m][3]);
;                     *(u32x2*)(Aout + (size_t)(row0 + ai * 128 + m) * FH + hc0 + 4 * n) = w; } } }
	v_rcp_f32_e32 v200, v193
	v_add_f32_e32 v193, 1.0, v201
	v_rcp_f32_e32 v201, v193
	v_or_b32_e32 v193, 1, v245
	v_pk_mul_f32 v[198:199], v[198:199], v[200:201]
	s_nop 0
	v_pk_mul_f32 v[196:197], v[196:197], v[198:199]
	v_pk_fma_f32 v[198:199], v[128:129], v[184:185], v[188:189]
	v_cvt_pk_bf16_f32 v195, v196, v197
	v_pk_fma_f32 v[198:199], v[132:133], v[180:181], v[198:199]
	v_mad_i64_i32 v[196:197], s[34:35], v193, s63, v[206:207]
	v_pk_fma_f32 v[152:153], v[152:153], v[176:177], v[198:199]
	v_lshl_add_u64 v[196:197], v[196:197], 0, v[204:205]
	v_mul_f32_e32 v193, 0xbfb8aa3b, v152
	v_exp_f32_e32 v193, v193
	v_mul_f32_e32 v198, 0xbfb8aa3b, v153
	v_exp_f32_e32 v198, v198
	global_store_dwordx2 v[196:197], v[194:195], off
	v_add_f32_e32 v193, 1.0, v193
	v_rcp_f32_e32 v194, v193
	v_add_f32_e32 v193, 1.0, v198
	v_rcp_f32_e32 v195, v193
	v_pk_fma_f32 v[198:199], v[136:137], v[168:169], v[172:173]
	v_pk_fma_f32 v[128:129], v[128:129], v[180:181], v[140:141]
	v_pk_fma_f32 v[198:199], v[144:145], v[164:165], v[198:199]
	v_pk_fma_f32 v[128:129], v[132:133], v[176:177], v[128:129]
	v_pk_fma_f32 v[156:157], v[156:157], v[160:161], v[198:199]
	v_pk_mul_f32 v[152:153], v[152:153], v[194:195]
	v_mul_f32_e32 v132, 0xbfb8aa3b, v128
	v_pk_mul_f32 v[152:153], v[156:157], v[152:153]
	v_pk_fma_f32 v[156:157], v[130:131], v[186:187], v[190:191]
	v_exp_f32_e32 v140, v132
	v_pk_fma_f32 v[132:133], v[142:143], v[186:187], v[190:191]
	v_pk_fma_f32 v[156:157], v[134:135], v[182:183], v[156:157]
	v_pk_fma_f32 v[130:131], v[130:131], v[182:183], v[132:133]
	v_pk_fma_f32 v[154:155], v[154:155], v[178:179], v[156:157]
	v_pk_fma_f32 v[130:131], v[134:135], v[178:179], v[130:131]
	v_mul_f32_e32 v156, 0xbfb8aa3b, v154
	v_mul_f32_e32 v141, 0xbfb8aa3b, v129
	v_mul_f32_e32 v132, 0xbfb8aa3b, v130
	v_mul_f32_e32 v133, 0xbfb8aa3b, v131
	v_exp_f32_e32 v157, v156
	v_mul_f32_e32 v156, 0xbfb8aa3b, v155
	v_exp_f32_e32 v141, v141
	v_exp_f32_e32 v132, v132
	v_exp_f32_e32 v133, v133
	v_exp_f32_e32 v193, v156
	v_add_f32_e32 v140, 1.0, v140
	v_add_f32_e32 v141, 1.0, v141
	v_add_f32_e32 v132, 1.0, v132
	v_add_f32_e32 v133, 1.0, v133
	v_cvt_pk_bf16_f32 v156, v152, v153
	v_add_f32_e32 v152, 1.0, v157
	v_add_f32_e32 v153, 1.0, v193
	v_rcp_f32_e32 v140, v140
	v_rcp_f32_e32 v141, v141
	v_rcp_f32_e32 v132, v132
	v_rcp_f32_e32 v133, v133
	v_rcp_f32_e32 v152, v152
	v_rcp_f32_e32 v153, v153
	v_pk_fma_f32 v[142:143], v[150:151], v[170:171], v[174:175]
	v_pk_fma_f32 v[194:195], v[138:139], v[170:171], v[174:175]
	v_pk_fma_f32 v[136:137], v[136:137], v[164:165], v[148:149]
	v_pk_fma_f32 v[134:135], v[138:139], v[166:167], v[142:143]
	v_pk_fma_f32 v[194:195], v[146:147], v[166:167], v[194:195]
	v_pk_fma_f32 v[136:137], v[144:145], v[160:161], v[136:137]
	v_pk_mul_f32 v[128:129], v[128:129], v[140:141]
	v_pk_fma_f32 v[134:135], v[146:147], v[162:163], v[134:135]
	v_pk_mul_f32 v[130:131], v[130:131], v[132:133]
	v_pk_fma_f32 v[158:159], v[158:159], v[162:163], v[194:195]
	v_pk_mul_f32 v[152:153], v[154:155], v[152:153]
	v_pk_mul_f32 v[128:129], v[136:137], v[128:129]
	v_pk_mul_f32 v[130:131], v[134:135], v[130:131]
	v_pk_mul_f32 v[152:153], v[158:159], v[152:153]
	v_cvt_pk_bf16_f32 v128, v128, v129
	v_cvt_pk_bf16_f32 v129, v130, v131
	v_or_b32_e32 v130, 3, v245
	v_cvt_pk_bf16_f32 v157, v152, v153
	v_or_b32_e32 v152, 2, v245
	v_mad_i64_i32 v[130:131], s[34:35], v130, s63, v[206:207]
	v_mad_i64_i32 v[152:153], s[34:35], v152, s63, v[206:207]
	v_lshl_add_u64 v[140:141], v[130:131], 0, v[204:205]
	v_lshl_add_u64 v[152:153], v[152:153], 0, v[204:205]
	global_store_dwordx2 v[140:141], v[128:129], off
	v_mov_b32_e32 v193, 0
	v_mov_b32_e32 v194, 0
	v_mov_b32_e32 v195, 0
	v_mov_b32_e32 v136, 0
	v_mov_b32_e32 v137, 0
	v_mov_b32_e32 v138, 0
	v_mov_b32_e32 v139, 0
	v_mov_b32_e32 v128, 0
	v_mov_b32_e32 v129, 0
	v_mov_b32_e32 v130, 0
	v_mov_b32_e32 v131, 0
	v_mov_b32_e32 v132, 0
	v_mov_b32_e32 v133, 0
	v_mov_b32_e32 v134, 0
	v_mov_b32_e32 v135, 0
	global_store_dwordx2 v[152:153], v[156:157], off
	s_and_saveexec_b64 s[34:35], s[22:23]
	s_cbranch_execz .LBB0_1951
	ds_read_b128 v[132:135], v236 offset:2048
	ds_read_b128 v[136:139], v236 offset:2560
	ds_read_b128 v[128:131], v236 offset:3072
	ds_read_b128 v[192:195], v236 offset:3584

; __device__ __forceinline__ float sigmoidf_(float x) { return __builtin_amdgcn_rcpf(1.0f + __expf(-x)); }
;     __device__ __forceinline__ void operator()(AccRef acc, const Unit& u, int wr, int wc, int fr, int fq) const {
;     ...
;                 float o[4][4];
; #pragma unroll
;                 for (int j = 0; j < 4; ++j) {
;                     const float v0 = acc[ai][0][0][n][j], v1 = acc[ai][0][1][n][j], v2 = acc[ai][0][2][n][j], v3 = acc[ai][0][3][n][j];
;                     const float g0 = acc[ai][1][0][n][j], g1 = acc[ai][1][1][n][j], g2 = acc[ai][1][2][n][j], g3 = acc[ai][1][3][n][j];
;                     const float pv3 = dpp_upd<0x111>(h3v[j], v3), pv2 = dpp_upd<0x111>(h2v[j], v2), pg3 = dpp_upd<0x111>(h3g[j], g3), pg2 = dpp_upd<0x111>(h2g[j], g2);
;                     const float hv0 = bvv[j] + w2v[j] * v0 + w1v[j] * pv3 + w0v[j] * pv2, hv1 = bvv[j] + w2v[j] * v1 + w1v[j] * v0 + w0v[j] * pv3;
;                     const float hv2 = bvv[j] + w2v[j] * v2 + w1v[j] * v1 + w0v[j] * v0, hv3 = bvv[j] + w2v[j] * v3 + w1v[j] * v2 + w0v[j] * v1;
;                     const float hg0 = bvg[j] + w2g[j] * g0 + w1g[j] * pg3 + w0g[j] * pg2, hg1 = bvg[j] + w2g[j] * g1 + w1g[j] * g0 + w0g[j] * pg3;
;                     const float hg2 = bvg[j] + w2g[j] * g2 + w1g[j] * g1 + w0g[j] * g0, hg3 = bvg[j] + w2g[j] * g3 + w1g[j] * g2 + w0g[j] * g1;
;                     o[0][j] = hg0 * sigmoidf_(hg0) * hv0; o[1][j] = hg1 * sigmoidf_(hg1) * hv1; o[2][j] = hg2 * sigmoidf_(hg2) * hv2; o[3][j] = hg3 * sigmoidf_(hg3) * hv3; }
; #pragma unroll
;                 for (int m = 0; m < 4; ++m) { u32x2 w; w.x = cvt_pk_bf16(o[m][0], o[m][1]); w.y = cvt_pk_bf16(o[m][2], o[m][3]);
;                     *(u32x2*)(Aout + (size_t)(row0 + ai * 128 + m) * FH + hc0 + 4 * n) = w; } } }
.LBB0_1953:
	s_or_b64 exec, exec, s[34:35]
	s_waitcnt lgkmcnt(0)
	v_mov_b32_dpp v70, v44 row_shr:1 row_mask:0xf bank_mask:0xf
	v_mov_b32_dpp v71, v45 row_shr:1 row_mask:0xf bank_mask:0xf
	s_waitcnt vmcnt(8)
	v_pk_fma_f32 v[84:85], v[56:57], v[120:121], v[124:125]
	v_mov_b32_dpp v78, v32 row_shr:1 row_mask:0xf bank_mask:0xf
	v_mov_b32_dpp v79, v33 row_shr:1 row_mask:0xf bank_mask:0xf
	v_pk_fma_f32 v[84:85], v[116:117], v[70:71], v[84:85]
	v_mov_b32_dpp v66, v52 row_shr:1 row_mask:0xf bank_mask:0xf
	v_pk_fma_f32 v[78:79], v[112:113], v[78:79], v[84:85]
	v_mov_b32_dpp v67, v53 row_shr:1 row_mask:0xf bank_mask:0xf
	v_mul_f32_e32 v65, 0xbfb8aa3b, v78
	v_exp_f32_e32 v65, v65
	v_mul_f32_e32 v84, 0xbfb8aa3b, v79
	v_exp_f32_e32 v85, v84
	v_pk_fma_f32 v[86:87], v[60:61], v[104:105], v[108:109]
	v_add_f32_e32 v65, 1.0, v65
	v_rcp_f32_e32 v84, v65
	v_add_f32_e32 v65, 1.0, v85
	v_rcp_f32_e32 v85, v65
	v_mov_b32_dpp v74, v40 row_shr:1 row_mask:0xf bank_mask:0xf
	v_mov_b32_dpp v75, v41 row_shr:1 row_mask:0xf bank_mask:0xf
	v_pk_fma_f32 v[86:87], v[100:101], v[66:67], v[86:87]
	v_pk_mul_f32 v[78:79], v[78:79], v[84:85]
	v_pk_fma_f32 v[74:75], v[96:97], v[74:75], v[86:87]
	v_mov_b32_dpp v72, v46 row_shr:1 row_mask:0xf bank_mask:0xf
	v_mov_b32_dpp v73, v47 row_shr:1 row_mask:0xf bank_mask:0xf
	v_pk_mul_f32 v[74:75], v[74:75], v[78:79]
	v_pk_fma_f32 v[78:79], v[58:59], v[122:123], v[126:127]
	v_mov_b32_dpp v80, v34 row_shr:1 row_mask:0xf bank_mask:0xf
	v_mov_b32_dpp v81, v35 row_shr:1 row_mask:0xf bank_mask:0xf
	v_pk_fma_f32 v[78:79], v[118:119], v[72:73], v[78:79]
	v_mov_b32_dpp v68, v54 row_shr:1 row_mask:0xf bank_mask:0xf
	v_pk_fma_f32 v[78:79], v[114:115], v[80:81], v[78:79]
	v_mov_b32_dpp v69, v55 row_shr:1 row_mask:0xf bank_mask:0xf
	v_mul_f32_e32 v65, 0xbfb8aa3b, v78
	v_exp_f32_e32 v65, v65
	v_mul_f32_e32 v80, 0xbfb8aa3b, v79
	v_exp_f32_e32 v81, v80
	v_pk_fma_f32 v[84:85], v[62:63], v[106:107], v[110:111]
	v_add_f32_e32 v65, 1.0, v65
	v_rcp_f32_e32 v80, v65
	v_add_f32_e32 v65, 1.0, v81
	v_rcp_f32_e32 v81, v65
	v_mov_b32_dpp v76, v42 row_shr:1 row_mask:0xf bank_mask:0xf
	v_mov_b32_dpp v77, v43 row_shr:1 row_mask:0xf bank_mask:0xf
	v_pk_fma_f32 v[84:85], v[102:103], v[68:69], v[84:85]
	v_pk_mul_f32 v[78:79], v[78:79], v[80:81]
	v_pk_fma_f32 v[76:77], v[98:99], v[76:77], v[84:85]
	v_cvt_pk_bf16_f32 v74, v74, v75
	v_pk_mul_f32 v[76:77], v[76:77], v[78:79]
	v_pk_fma_f32 v[44:45], v[44:45], v[120:121], v[124:125]
	v_cvt_pk_bf16_f32 v75, v76, v77
	v_pk_fma_f32 v[76:77], v[36:37], v[120:121], v[124:125]
	global_store_dwordx2 v[202:203], v[74:75], off offset:8
	v_pk_fma_f32 v[76:77], v[56:57], v[116:117], v[76:77]
	v_pk_fma_f32 v[52:53], v[52:53], v[104:105], v[108:109]
	v_pk_fma_f32 v[70:71], v[112:113], v[70:71], v[76:77]
	s_nop 0
	v_mul_f32_e32 v65, 0xbfb8aa3b, v70
	v_exp_f32_e32 v65, v65
	v_mul_f32_e32 v76, 0xbfb8aa3b, v71
	v_exp_f32_e32 v76, v76
	v_add_f32_e32 v65, 1.0, v65
	v_rcp_f32_e32 v74, v65
	v_add_f32_e32 v65, 1.0, v76
	v_rcp_f32_e32 v75, v65
	v_pk_fma_f32 v[76:77], v[48:49], v[104:105], v[108:109]
	v_pk_mul_f32 v[70:71], v[70:71], v[74:75]
	v_pk_fma_f32 v[76:77], v[60:61], v[100:101], v[76:77]
	v_pk_fma_f32 v[74:75], v[50:51], v[106:107], v[110:111]
	v_pk_fma_f32 v[66:67], v[96:97], v[66:67], v[76:77]
	v_pk_fma_f32 v[74:75], v[62:63], v[102:103], v[74:75]
	v_pk_mul_f32 v[66:67], v[66:67], v[70:71]
	v_pk_fma_f32 v[70:71], v[38:39], v[122:123], v[126:127]
	v_pk_fma_f32 v[68:69], v[98:99], v[68:69], v[74:75]
	v_pk_fma_f32 v[70:71], v[58:59], v[118:119], v[70:71]
	v_cvt_pk_bf16_f32 v66, v66, v67
	v_pk_fma_f32 v[70:71], v[114:115], v[72:73], v[70:71]
	s_nop 0
	v_mul_f32_e32 v65, 0xbfb8aa3b, v70
	v_exp_f32_e32 v65, v65
; #define LAS __attribute__((address_space(3)))
; __device__ __forceinline__ float sigmoidf_(float x) { return __builtin_amdgcn_rcpf(1.0f + __expf(-x)); }
;     __device__ __forceinline__ void operator()(AccRef acc, const Unit& u, int wr, int wc, int fr, int fq) const {
;     ...
;                 f32x4 h2v = (f32x4){0.f, 0.f, 0.f, 0.f}, h3v = h2v, h2g = h2v, h3g = h2v;
;                 const int pb = ai * 2 + wr - 1;
;                 if (pb >= 0 && fr == 0) { const LAS float* xp = xch + (pb * 2) * 256 + clb + 4 * n;
;                     h2v = *(const LAS f32x4*)(xp); h3v = *(const LAS f32x4*)(xp + 256); h2g = *(const LAS f32x4*)(xp + 128); h3g = *(const LAS f32x4*)(xp + 256 + 128); }
;                 float o[4][4];
; #pragma unroll
;                 for (int j = 0; j < 4; ++j) {
;                     const float v0 = acc[ai][0][0][n][j], v1 = acc[ai][0][1][n][j], v2 = acc[ai][0][2][n][j], v3 = acc[ai][0][3][n][j];
;                     const float g0 = acc[ai][1][0][n][j], g1 = acc[ai][1][1][n][j], g2 = acc[ai][1][2][n][j], g3 = acc[ai][1][3][n][j];
;                     const float pv3 = dpp_upd<0x111>(h3v[j], v3), pv2 = dpp_upd<0x111>(h2v[j], v2), pg3 = dpp_upd<0x111>(h3g[j], g3), pg2 = dpp_upd<0x111>(h2g[j], g2);
;                     const float hv0 = bvv[j] + w2v[j] * v0 + w1v[j] * pv3 + w0v[j] * pv2, hv1 = bvv[j] + w2v[j] * v1 + w1v[j] * v0 + w0v[j] * pv3;
;                     const float hv2 = bvv[j] + w2v[j] * v2 + w1v[j] * v1 + w0v[j] * v0, hv3 = bvv[j] + w2v[j] * v3 + w1v[j] * v2 + w0v[j] * v1;
;                     const float hg0 = bvg[j] + w2g[j] * g0 + w1g[j] * pg3 + w0g[j] * pg2, hg1 = bvg[j] + w2g[j] * g1 + w1g[j] * g0 + w0g[j] * pg3;
;                     const float hg2 = bvg[j] + w2g[j] * g2 + w1g[j] * g1 + w0g[j] * g0, hg3 = bvg[j] + w2g[j] * g3 + w1g[j] * g2 + w0g[j] * g1;
;                     o[0][j] = hg0 * sigmoidf_(hg0) * hv0; o[1][j] = hg1 * sigmoidf_(hg1) * hv1; o[2][j] = hg2 * sigmoidf_(hg2) * hv2; o[3][j] = hg3 * sigmoidf_(hg3) * hv3; }
; #pragma unroll
;                 for (int m = 0; m < 4; ++m) { u32x2 w; w.x = cvt_pk_bf16(o[m][0], o[m][1]); w.y = cvt_pk_bf16(o[m][2], o[m][3]);
;                     *(u32x2*)(Aout + (size_t)(row0 + ai * 128 + m) * FH + hc0 + 4 * n) = w; } } }
	v_mul_f32_e32 v72, 0xbfb8aa3b, v71
	v_exp_f32_e32 v73, v72
	v_add_f32_e32 v65, 1.0, v65
	v_rcp_f32_e32 v72, v65
	v_add_f32_e32 v65, 1.0, v73
	v_rcp_f32_e32 v73, v65
	s_nop 0
	v_pk_mul_f32 v[70:71], v[70:71], v[72:73]
	s_nop 0
	v_pk_mul_f32 v[68:69], v[68:69], v[70:71]
	s_nop 0
	v_cvt_pk_bf16_f32 v67, v68, v69
	v_pk_fma_f32 v[68:69], v[32:33], v[120:121], v[124:125]
	global_store_dwordx2 v[196:197], v[66:67], off offset:8
	v_pk_fma_f32 v[68:69], v[36:37], v[116:117], v[68:69]
	v_pk_fma_f32 v[32:33], v[32:33], v[116:117], v[44:45]
	v_pk_fma_f32 v[56:57], v[56:57], v[112:113], v[68:69]
	v_pk_fma_f32 v[32:33], v[36:37], v[112:113], v[32:33]
	v_mul_f32_e32 v65, 0xbfb8aa3b, v56
	v_exp_f32_e32 v65, v65
	v_mul_f32_e32 v68, 0xbfb8aa3b, v57
	v_exp_f32_e32 v68, v68
	v_mul_f32_e32 v36, 0xbfb8aa3b, v32
	v_add_f32_e32 v65, 1.0, v65
	v_rcp_f32_e32 v66, v65
	v_add_f32_e32 v65, 1.0, v68
	v_rcp_f32_e32 v67, v65
	v_pk_fma_f32 v[68:69], v[40:41], v[104:105], v[108:109]
	v_exp_f32_e32 v44, v36
	v_pk_fma_f32 v[68:69], v[48:49], v[100:101], v[68:69]
	v_pk_mul_f32 v[56:57], v[56:57], v[66:67]
	v_pk_fma_f32 v[60:61], v[60:61], v[96:97], v[68:69]
	v_pk_fma_f32 v[36:37], v[46:47], v[122:123], v[126:127]
	v_pk_mul_f32 v[56:57], v[60:61], v[56:57]
	v_pk_fma_f32 v[60:61], v[34:35], v[122:123], v[126:127]
	v_pk_fma_f32 v[34:35], v[34:35], v[118:119], v[36:37]
	v_pk_fma_f32 v[60:61], v[38:39], v[118:119], v[60:61]
	v_pk_fma_f32 v[34:35], v[38:39], v[114:115], v[34:35]
	v_pk_fma_f32 v[58:59], v[58:59], v[114:115], v[60:61]
	v_mul_f32_e32 v45, 0xbfb8aa3b, v33
	v_mul_f32_e32 v60, 0xbfb8aa3b, v58
	v_mul_f32_e32 v36, 0xbfb8aa3b, v34
	v_mul_f32_e32 v37, 0xbfb8aa3b, v35
	v_exp_f32_e32 v60, v60
	v_mul_f32_e32 v61, 0xbfb8aa3b, v59
	v_exp_f32_e32 v45, v45
	v_exp_f32_e32 v36, v36
	v_exp_f32_e32 v37, v37
	v_exp_f32_e32 v61, v61
	v_cvt_pk_bf16_f32 v56, v56, v57
	v_add_f32_e32 v57, 1.0, v60
	v_add_f32_e32 v44, 1.0, v44
	v_add_f32_e32 v45, 1.0, v45
	v_add_f32_e32 v36, 1.0, v36
	v_add_f32_e32 v37, 1.0, v37
	v_rcp_f32_e32 v60, v57
	v_add_f32_e32 v57, 1.0, v61
	v_rcp_f32_e32 v44, v44
	v_rcp_f32_e32 v45, v45
	v_rcp_f32_e32 v36, v36
	v_rcp_f32_e32 v37, v37
	v_rcp_f32_e32 v61, v57
	v_pk_fma_f32 v[46:47], v[54:55], v[106:107], v[110:111]
	v_pk_fma_f32 v[66:67], v[42:43], v[106:107], v[110:111]
	v_pk_fma_f32 v[40:41], v[40:41], v[100:101], v[52:53]
	v_pk_fma_f32 v[38:39], v[42:43], v[102:103], v[46:47]
	v_pk_fma_f32 v[66:67], v[50:51], v[102:103], v[66:67]
	v_pk_fma_f32 v[40:41], v[48:49], v[96:97], v[40:41]
	v_pk_mul_f32 v[32:33], v[32:33], v[44:45]
	v_pk_fma_f32 v[38:39], v[50:51], v[98:99], v[38:39]
	v_pk_mul_f32 v[34:35], v[34:35], v[36:37]
	v_pk_fma_f32 v[62:63], v[62:63], v[98:99], v[66:67]
	v_pk_mul_f32 v[58:59], v[58:59], v[60:61]
	v_pk_mul_f32 v[32:33], v[40:41], v[32:33]
	v_pk_mul_f32 v[34:35], v[38:39], v[34:35]
	v_pk_mul_f32 v[58:59], v[62:63], v[58:59]
	v_cvt_pk_bf16_f32 v32, v32, v33
	v_cvt_pk_bf16_f32 v33, v34, v35
	v_cvt_pk_bf16_f32 v57, v58, v59
	global_store_dwordx2 v[140:141], v[32:33], off offset:8
	v_mov_b32_e32 v65, 0
	v_mov_b32_e32 v66, 0
	v_mov_b32_e32 v67, 0
	v_mov_b32_e32 v40, 0
	v_mov_b32_e32 v41, 0
	v_mov_b32_e32 v42, 0
	v_mov_b32_e32 v43, 0
	v_mov_b32_e32 v32, 0
	v_mov_b32_e32 v33, 0
	v_mov_b32_e32 v34, 0
	v_mov_b32_e32 v35, 0
	v_mov_b32_e32 v36, 0
	v_mov_b32_e32 v37, 0
	v_mov_b32_e32 v38, 0
	v_mov_b32_e32 v39, 0
	global_store_dwordx2 v[152:153], v[56:57], off offset:8
	s_and_saveexec_b64 s[34:35], s[22:23]
	s_cbranch_execz .LBB0_1936
	ds_read_b128 v[36:39], v236 offset:2064
	ds_read_b128 v[40:43], v236 offset:2576
	ds_read_b128 v[32:35], v236 offset:3088
	ds_read_b128 v[64:67], v236 offset:3600
	s_branch .LBB0_1936
